# baseline (speedup 1.0000x reference)
; #define PG8_STAGE(bufoff, gbase, voff) do { _Pragma("unroll") for (int _i = 0; _i < 2; ++_i) \
;         __builtin_amdgcn_global_load_lds((const unsigned*)((const char*)(gbase) + (voff)[_i]), (PG8_LAS unsigned*)(lds + (bufoff) + ldsw + _i * 8192), 16, 0, 0); } while (0)
; #define PG8_LDA(dst, b, h) do { _Pragma("unroll") for (int m = 0; m < 4; ++m) _Pragma("unroll") for (int k = 0; k < 2; ++k) dst[m][k] = *(const PG8_LAS bf16x8*)(lds + PG8_SA(b, h) + aoff + m * 2048 + k * 1024); } while (0)
; #define PG8_LDB(dst, b, h) do { _Pragma("unroll") for (int n = 0; n < 2; ++n) _Pragma("unroll") for (int k = 0; k < 2; ++k) dst[n][k] = *(const PG8_LAS bf16x8*)(lds + PG8_SB(b, h) + boff + n * 2048 + k * 1024); } while (0)
; #define PG8_MMA(ai, bj, At, Bt) do { __builtin_amdgcn_s_setprio(1); _Pragma("unroll") for (int m = 0; m < 4; ++m) _Pragma("unroll") for (int n = 0; n < 2; ++n) _Pragma("unroll") for (int k = 0; k < 2; ++k) \
;         acc[ai][bj][m][n] = __builtin_amdgcn_mfma_f32_16x16x32_bf16(Bt[n][k], At[m][k], acc[ai][bj][m][n], 0, 0, 0); __builtin_amdgcn_s_setprio(0); } while (0)
; #define PG8_WAIT_V(n) asm volatile("s_waitcnt vmcnt(" #n ")" ::: "memory")
; #define PG8_BAR __builtin_amdgcn_s_barrier()
; template <class Epi, class Sched, bool ALIGN_EPI = false, bool SP2 = false>
; __device__ __forceinline__ void gemm_phase(PG8_LAS unsigned char* lds, const Gemm g, const Sched& S, const Epi& E, const int wid_in) {
;     ...
;         for (int t = 0; t < nt; t += 2) {
;             const bool last = (t == nt - 2);
;             const char* a1 = cA + (size_t)(t + 1) * kstep;
;             const char* a2 = last ? nA : cA + (size_t)(t + 2) * kstep; const char* b2 = last ? nB : cB + (size_t)(t + 2) * kstep;
;             const char* a3 = a2 + kstep; const char* b3 = b2 + kstep;
;             if (last && has_next) S.a_ready(nxt);
;             if constexpr (SP2) {
;             PG8_LDB(B0, 0, 0); PG8_LDB(B1, 0, 1); PG8_SCHED; PG8_LDA(At, 0, 0); PG8_STAGE(PG8_SA(1, 1), a1 + hstep, voffA);
;             PG8_WAIT_V(8); PG8_WAIT_L(0); PG8_BAR; PG8_MMA(0, 0, At, B0); PG8_MMA(0, 1, At, B1); PG8_BAR; PG8_SCHED;
;             PG8_LDA(At, 0, 1); PG8_STAGE(PG8_SB(0, 0), b2, voffB); PG8_STAGE(PG8_SB(0, 1), b2 + hstep, voffB); PG8_STAGE(PG8_SA(0, 0), a2, voffA);
;             PG8_WAIT_V(8); PG8_WAIT_L(0); PG8_BAR; PG8_MMA(1, 0, At, B0); PG8_MMA(1, 1, At, B1); PG8_BAR; PG8_SCHED;
.LBB0_160:
	s_add_u32 s24, s42, 0xfff80080
	s_addc_u32 s25, s43, -1
	s_add_i32 s26, 0, 0x10000
	s_cmp_eq_u32 s39, 28
	s_cselect_b32 s47, s6, s25
	s_cselect_b32 s46, s7, s24
	v_add_u32_e32 v158, s26, v162
	s_cselect_b32 s45, s14, s35
	s_cselect_b32 s44, s15, s34
	s_add_i32 s27, 0, 0x14000
	ds_read_b128 v[146:149], v158
	ds_read_b128 v[150:153], v158 offset:1024
	ds_read_b128 v[154:157], v158 offset:2048
	ds_read_b128 v[164:167], v158 offset:3072
	v_add_u32_e32 v158, s27, v162
	ds_read_b128 v[168:171], v158
	ds_read_b128 v[172:175], v158 offset:1024
	ds_read_b128 v[176:179], v158 offset:2048
	ds_read_b128 v[186:189], v158 offset:3072
	v_lshl_add_u64 v[158:159], s[42:43], 0, v[142:143]
	s_add_i32 m0, s76, 0xc000
	ds_read_b128 v[190:193], v183
	ds_read_b128 v[194:197], v183 offset:1024
	ds_read_b128 v[198:201], v183 offset:2048
	ds_read_b128 v[202:205], v183 offset:3072
	ds_read_b128 v[206:209], v183 offset:4096
	ds_read_b128 v[210:213], v183 offset:5120
	ds_read_b128 v[214:217], v183 offset:6144
	ds_read_b128 v[218:221], v183 offset:7168
	global_load_lds_dwordx4 v[158:159], off
	v_lshl_add_u64 v[158:159], s[42:43], 0, v[144:145]
	s_add_i32 m0, s76, 0xe000
	s_nop 0
	global_load_lds_dwordx4 v[158:159], off
	s_waitcnt vmcnt(8)
	s_waitcnt lgkmcnt(0)
	s_barrier
	s_setprio 1
	s_waitcnt lgkmcnt(0)
	v_mfma_f32_16x16x32_bf16 v[124:127], v[146:149], v[190:193], v[124:127]
	v_mfma_f32_16x16x32_bf16 v[120:123], v[154:157], v[190:193], v[120:123]
	v_mfma_f32_16x16x32_bf16 v[108:111], v[146:149], v[198:201], v[108:111]
	v_mfma_f32_16x16x32_bf16 v[104:107], v[154:157], v[198:201], v[104:107]
	v_mfma_f32_16x16x32_bf16 v[92:95], v[146:149], v[206:209], v[92:95]
	v_mfma_f32_16x16x32_bf16 v[88:91], v[154:157], v[206:209], v[88:91]
	v_mfma_f32_16x16x32_bf16 v[76:79], v[146:149], v[214:217], v[76:79]
	v_mfma_f32_16x16x32_bf16 v[72:75], v[154:157], v[214:217], v[72:75]
	v_mfma_f32_16x16x32_bf16 v[124:127], v[150:153], v[194:197], v[124:127]
	v_mfma_f32_16x16x32_bf16 v[120:123], v[164:167], v[194:197], v[120:123]
	v_mfma_f32_16x16x32_bf16 v[108:111], v[150:153], v[202:205], v[108:111]
	v_mfma_f32_16x16x32_bf16 v[104:107], v[164:167], v[202:205], v[104:107]
	v_mfma_f32_16x16x32_bf16 v[92:95], v[150:153], v[210:213], v[92:95]
	v_mfma_f32_16x16x32_bf16 v[88:91], v[164:167], v[210:213], v[88:91]
	v_mfma_f32_16x16x32_bf16 v[76:79], v[150:153], v[218:221], v[76:79]
	v_mfma_f32_16x16x32_bf16 v[72:75], v[164:167], v[218:221], v[72:75]
	s_setprio 0
	s_setprio 1
	v_mfma_f32_16x16x32_bf16 v[116:119], v[168:171], v[190:193], v[116:119]
	v_mfma_f32_16x16x32_bf16 v[112:115], v[176:179], v[190:193], v[112:115]
	v_mfma_f32_16x16x32_bf16 v[100:103], v[168:171], v[198:201], v[100:103]
	v_mfma_f32_16x16x32_bf16 v[96:99], v[176:179], v[198:201], v[96:99]
	v_mfma_f32_16x16x32_bf16 v[84:87], v[168:171], v[206:209], v[84:87]
	v_mfma_f32_16x16x32_bf16 v[80:83], v[176:179], v[206:209], v[80:83]
	v_mfma_f32_16x16x32_bf16 v[68:71], v[168:171], v[214:217], v[68:71]
	v_mfma_f32_16x16x32_bf16 v[64:67], v[176:179], v[214:217], v[64:67]
	v_mfma_f32_16x16x32_bf16 v[116:119], v[172:175], v[194:197], v[116:119]
	v_mfma_f32_16x16x32_bf16 v[112:115], v[186:189], v[194:197], v[112:115]
	v_mfma_f32_16x16x32_bf16 v[100:103], v[172:175], v[202:205], v[100:103]
	v_mfma_f32_16x16x32_bf16 v[96:99], v[186:189], v[202:205], v[96:99]
	v_mfma_f32_16x16x32_bf16 v[84:87], v[172:175], v[210:213], v[84:87]
	v_mfma_f32_16x16x32_bf16 v[80:83], v[186:189], v[210:213], v[80:83]
	v_mfma_f32_16x16x32_bf16 v[68:71], v[172:175], v[218:221], v[68:71]
	v_mfma_f32_16x16x32_bf16 v[64:67], v[186:189], v[218:221], v[64:67]
	s_setprio 0
	s_barrier
	s_add_i32 s24, s26, s75
	v_lshl_add_u64 v[158:159], s[44:45], 0, v[130:131]
	s_mov_b32 m0, s24
	ds_read_b128 v[190:193], v183 offset:16384
	ds_read_b128 v[194:197], v183 offset:17408
	ds_read_b128 v[198:201], v183 offset:18432
	ds_read_b128 v[202:205], v183 offset:19456
	ds_read_b128 v[206:209], v183 offset:20480
	ds_read_b128 v[210:213], v183 offset:21504
	ds_read_b128 v[214:217], v183 offset:22528
	ds_read_b128 v[218:221], v183 offset:23552
	global_load_lds_dwordx4 v[158:159], off
	s_add_i32 m0, s24, 0x2000
	s_add_u32 s24, s44, 0x80000
	v_lshl_add_u64 v[180:181], s[44:45], 0, v[134:135]
	s_addc_u32 s25, s45, 0
	s_add_i32 s26, s27, s75
	global_load_lds_dwordx4 v[180:181], off
	v_lshl_add_u64 v[222:223], s[24:25], 0, v[130:131]
	s_mov_b32 m0, s26
	v_lshl_add_u64 v[224:225], s[46:47], 0, v[132:133]
	global_load_lds_dwordx4 v[222:223], off
	v_lshl_add_u64 v[222:223], s[24:25], 0, v[134:135]
	s_add_i32 m0, s26, 0x2000
	s_nop 0
	global_load_lds_dwordx4 v[222:223], off
	v_lshl_add_u64 v[222:223], s[46:47], 0, v[128:129]
	s_mov_b32 m0, s76
	s_nop 0
	global_load_lds_dwordx4 v[222:223], off
	s_mov_b32 m0, s77
	s_nop 0
	global_load_lds_dwordx4 v[224:225], off
	s_waitcnt vmcnt(8)
	s_waitcnt lgkmcnt(0)
	s_barrier
; #define PG8_STAGE(bufoff, gbase, voff) do { _Pragma("unroll") for (int _i = 0; _i < 2; ++_i) \
;         __builtin_amdgcn_global_load_lds((const unsigned*)((const char*)(gbase) + (voff)[_i]), (PG8_LAS unsigned*)(lds + (bufoff) + ldsw + _i * 8192), 16, 0, 0); } while (0)
; #define PG8_LDA(dst, b, h) do { _Pragma("unroll") for (int m = 0; m < 4; ++m) _Pragma("unroll") for (int k = 0; k < 2; ++k) dst[m][k] = *(const PG8_LAS bf16x8*)(lds + PG8_SA(b, h) + aoff + m * 2048 + k * 1024); } while (0)
; #define PG8_LDB(dst, b, h) do { _Pragma("unroll") for (int n = 0; n < 2; ++n) _Pragma("unroll") for (int k = 0; k < 2; ++k) dst[n][k] = *(const PG8_LAS bf16x8*)(lds + PG8_SB(b, h) + boff + n * 2048 + k * 1024); } while (0)
; #define PG8_MMA(ai, bj, At, Bt) do { __builtin_amdgcn_s_setprio(1); _Pragma("unroll") for (int m = 0; m < 4; ++m) _Pragma("unroll") for (int n = 0; n < 2; ++n) _Pragma("unroll") for (int k = 0; k < 2; ++k) \
;         acc[ai][bj][m][n] = __builtin_amdgcn_mfma_f32_16x16x32_bf16(Bt[n][k], At[m][k], acc[ai][bj][m][n], 0, 0, 0); __builtin_amdgcn_s_setprio(0); } while (0)
; #define PG8_WAIT_V(n) asm volatile("s_waitcnt vmcnt(" #n ")" ::: "memory")
; #define PG8_WAIT_L(n) asm volatile("s_waitcnt lgkmcnt(" #n ")" ::: "memory")
; #define PG8_BAR __builtin_amdgcn_s_barrier()
; #define PG8_SCHED __builtin_amdgcn_sched_barrier(0)
; template <class Epi, class Sched, bool ALIGN_EPI = false, bool SP2 = false>
; __device__ __forceinline__ void gemm_phase(PG8_LAS unsigned char* lds, const Gemm g, const Sched& S, const Epi& E, const int wid_in) {
;     ...
;             PG8_WAIT_V(8); PG8_WAIT_L(0); PG8_BAR; PG8_MMA(1, 0, At, B0); PG8_MMA(1, 1, At, B1); PG8_BAR; PG8_SCHED;
;             PG8_LDB(B0, 1, 0); PG8_LDB(B1, 1, 1); PG8_SCHED; PG8_LDA(At, 1, 0); PG8_STAGE(PG8_SA(0, 1), a2 + hstep, voffA);
;             PG8_WAIT_V(8); PG8_WAIT_L(0); PG8_BAR; PG8_MMA(0, 0, At, B0); PG8_MMA(0, 1, At, B1); PG8_BAR; PG8_SCHED;
	s_setprio 1
	s_waitcnt lgkmcnt(0)
	v_mfma_f32_16x16x32_bf16 v[60:63], v[146:149], v[190:193], v[60:63]
	v_mfma_f32_16x16x32_bf16 v[56:59], v[154:157], v[190:193], v[56:59]
	v_mfma_f32_16x16x32_bf16 v[44:47], v[146:149], v[198:201], v[44:47]
	v_mfma_f32_16x16x32_bf16 v[40:43], v[154:157], v[198:201], v[40:43]
	v_mfma_f32_16x16x32_bf16 v[28:31], v[146:149], v[206:209], v[28:31]
	v_mfma_f32_16x16x32_bf16 v[24:27], v[154:157], v[206:209], v[24:27]
	v_mfma_f32_16x16x32_bf16 v[12:15], v[146:149], v[214:217], v[12:15]
	v_mfma_f32_16x16x32_bf16 v[8:11], v[154:157], v[214:217], v[8:11]
	v_mfma_f32_16x16x32_bf16 v[60:63], v[150:153], v[194:197], v[60:63]
	v_mfma_f32_16x16x32_bf16 v[56:59], v[164:167], v[194:197], v[56:59]
	v_mfma_f32_16x16x32_bf16 v[44:47], v[150:153], v[202:205], v[44:47]
	v_mfma_f32_16x16x32_bf16 v[40:43], v[164:167], v[202:205], v[40:43]
	v_mfma_f32_16x16x32_bf16 v[28:31], v[150:153], v[210:213], v[28:31]
	v_mfma_f32_16x16x32_bf16 v[24:27], v[164:167], v[210:213], v[24:27]
	v_mfma_f32_16x16x32_bf16 v[12:15], v[150:153], v[218:221], v[12:15]
	v_mfma_f32_16x16x32_bf16 v[8:11], v[164:167], v[218:221], v[8:11]
	s_setprio 0
	s_setprio 1
	v_mfma_f32_16x16x32_bf16 v[52:55], v[168:171], v[190:193], v[52:55]
	v_mfma_f32_16x16x32_bf16 v[48:51], v[176:179], v[190:193], v[48:51]
	v_mfma_f32_16x16x32_bf16 v[36:39], v[168:171], v[198:201], v[36:39]
	v_mfma_f32_16x16x32_bf16 v[32:35], v[176:179], v[198:201], v[32:35]
	v_mfma_f32_16x16x32_bf16 v[20:23], v[168:171], v[206:209], v[20:23]
	v_mfma_f32_16x16x32_bf16 v[16:19], v[176:179], v[206:209], v[16:19]
	v_mfma_f32_16x16x32_bf16 v[4:7], v[168:171], v[214:217], v[4:7]
	v_mfma_f32_16x16x32_bf16 v[0:3], v[176:179], v[214:217], v[0:3]
	v_mfma_f32_16x16x32_bf16 v[52:55], v[172:175], v[194:197], v[52:55]
	v_mfma_f32_16x16x32_bf16 v[48:51], v[186:189], v[194:197], v[48:51]
	v_mfma_f32_16x16x32_bf16 v[36:39], v[172:175], v[202:205], v[36:39]
	v_mfma_f32_16x16x32_bf16 v[32:35], v[186:189], v[202:205], v[32:35]
	v_mfma_f32_16x16x32_bf16 v[20:23], v[172:175], v[210:213], v[20:23]
	v_mfma_f32_16x16x32_bf16 v[16:19], v[186:189], v[210:213], v[16:19]
	v_mfma_f32_16x16x32_bf16 v[4:7], v[172:175], v[218:221], v[4:7]
	v_mfma_f32_16x16x32_bf16 v[0:3], v[186:189], v[218:221], v[0:3]
	s_setprio 0
	s_barrier
	s_add_i32 s26, 0, 0x18000
	v_add_u32_e32 v160, s26, v162
	s_add_i32 s27, 0, 0x1c000
	ds_read_b128 v[146:149], v160
	ds_read_b128 v[150:153], v160 offset:1024
	ds_read_b128 v[154:157], v160 offset:2048
	ds_read_b128 v[164:167], v160 offset:3072
	v_add_u32_e32 v160, s27, v162
	ds_read_b128 v[168:171], v160
	ds_read_b128 v[172:175], v160 offset:1024
	ds_read_b128 v[176:179], v160 offset:2048
	ds_read_b128 v[186:189], v160 offset:3072
	s_add_u32 s24, s46, 0x80000
	s_addc_u32 s25, s47, 0
	s_mov_b32 m0, s78
	v_lshl_add_u64 v[226:227], s[24:25], 0, v[128:129]
	ds_read_b128 v[190:193], v183 offset:32768
	ds_read_b128 v[194:197], v183 offset:33792
	ds_read_b128 v[198:201], v183 offset:34816
	ds_read_b128 v[202:205], v183 offset:35840
	ds_read_b128 v[206:209], v183 offset:36864
	ds_read_b128 v[210:213], v183 offset:37888
	ds_read_b128 v[214:217], v183 offset:38912
	ds_read_b128 v[218:221], v183 offset:39936
	global_load_lds_dwordx4 v[226:227], off
	v_lshl_add_u64 v[226:227], s[24:25], 0, v[132:133]
	s_mov_b32 m0, s79
	s_nop 0
	global_load_lds_dwordx4 v[226:227], off
	s_waitcnt vmcnt(8)
	s_waitcnt lgkmcnt(0)
	s_barrier
	s_setprio 1
	s_waitcnt lgkmcnt(0)
	v_mfma_f32_16x16x32_bf16 v[124:127], v[146:149], v[190:193], v[124:127]
	v_mfma_f32_16x16x32_bf16 v[120:123], v[154:157], v[190:193], v[120:123]
	v_mfma_f32_16x16x32_bf16 v[108:111], v[146:149], v[198:201], v[108:111]
	v_mfma_f32_16x16x32_bf16 v[104:107], v[154:157], v[198:201], v[104:107]
	v_mfma_f32_16x16x32_bf16 v[92:95], v[146:149], v[206:209], v[92:95]
	v_mfma_f32_16x16x32_bf16 v[88:91], v[154:157], v[206:209], v[88:91]
	v_mfma_f32_16x16x32_bf16 v[76:79], v[146:149], v[214:217], v[76:79]
	v_mfma_f32_16x16x32_bf16 v[72:75], v[154:157], v[214:217], v[72:75]
	v_mfma_f32_16x16x32_bf16 v[124:127], v[150:153], v[194:197], v[124:127]
	v_mfma_f32_16x16x32_bf16 v[120:123], v[164:167], v[194:197], v[120:123]
	v_mfma_f32_16x16x32_bf16 v[108:111], v[150:153], v[202:205], v[108:111]
	v_mfma_f32_16x16x32_bf16 v[104:107], v[164:167], v[202:205], v[104:107]
	v_mfma_f32_16x16x32_bf16 v[92:95], v[150:153], v[210:213], v[92:95]
	v_mfma_f32_16x16x32_bf16 v[88:91], v[164:167], v[210:213], v[88:91]
	v_mfma_f32_16x16x32_bf16 v[76:79], v[150:153], v[218:221], v[76:79]
	v_mfma_f32_16x16x32_bf16 v[72:75], v[164:167], v[218:221], v[72:75]
	s_setprio 0
	s_setprio 1
	v_mfma_f32_16x16x32_bf16 v[116:119], v[168:171], v[190:193], v[116:119]
	v_mfma_f32_16x16x32_bf16 v[112:115], v[176:179], v[190:193], v[112:115]
	v_mfma_f32_16x16x32_bf16 v[100:103], v[168:171], v[198:201], v[100:103]
	v_mfma_f32_16x16x32_bf16 v[96:99], v[176:179], v[198:201], v[96:99]
	v_mfma_f32_16x16x32_bf16 v[84:87], v[168:171], v[206:209], v[84:87]
	v_mfma_f32_16x16x32_bf16 v[80:83], v[176:179], v[206:209], v[80:83]
	v_mfma_f32_16x16x32_bf16 v[68:71], v[168:171], v[214:217], v[68:71]
	v_mfma_f32_16x16x32_bf16 v[64:67], v[176:179], v[214:217], v[64:67]
	v_mfma_f32_16x16x32_bf16 v[116:119], v[172:175], v[194:197], v[116:119]
	v_mfma_f32_16x16x32_bf16 v[112:115], v[186:189], v[194:197], v[112:115]
	v_mfma_f32_16x16x32_bf16 v[100:103], v[172:175], v[202:205], v[100:103]
	v_mfma_f32_16x16x32_bf16 v[96:99], v[186:189], v[202:205], v[96:99]
	v_mfma_f32_16x16x32_bf16 v[84:87], v[172:175], v[210:213], v[84:87]
	v_mfma_f32_16x16x32_bf16 v[80:83], v[186:189], v[210:213], v[80:83]
	v_mfma_f32_16x16x32_bf16 v[68:71], v[172:175], v[218:221], v[68:71]
	v_mfma_f32_16x16x32_bf16 v[64:67], v[186:189], v[218:221], v[64:67]
	s_setprio 0
	s_barrier
; #define PG8_STAGE(bufoff, gbase, voff) do { _Pragma("unroll") for (int _i = 0; _i < 2; ++_i) \
;         __builtin_amdgcn_global_load_lds((const unsigned*)((const char*)(gbase) + (voff)[_i]), (PG8_LAS unsigned*)(lds + (bufoff) + ldsw + _i * 8192), 16, 0, 0); } while (0)
; #define PG8_LDA(dst, b, h) do { _Pragma("unroll") for (int m = 0; m < 4; ++m) _Pragma("unroll") for (int k = 0; k < 2; ++k) dst[m][k] = *(const PG8_LAS bf16x8*)(lds + PG8_SA(b, h) + aoff + m * 2048 + k * 1024); } while (0)
; #define PG8_MMA(ai, bj, At, Bt) do { __builtin_amdgcn_s_setprio(1); _Pragma("unroll") for (int m = 0; m < 4; ++m) _Pragma("unroll") for (int n = 0; n < 2; ++n) _Pragma("unroll") for (int k = 0; k < 2; ++k) \
;         acc[ai][bj][m][n] = __builtin_amdgcn_mfma_f32_16x16x32_bf16(Bt[n][k], At[m][k], acc[ai][bj][m][n], 0, 0, 0); __builtin_amdgcn_s_setprio(0); } while (0)
; #define PG8_WAIT_V(n) asm volatile("s_waitcnt vmcnt(" #n ")" ::: "memory")
; #define PG8_WAIT_L(n) asm volatile("s_waitcnt lgkmcnt(" #n ")" ::: "memory")
; #define PG8_BAR __builtin_amdgcn_s_barrier()
; #define PG8_SCHED __builtin_amdgcn_sched_barrier(0)
; template <class Epi, class Sched, bool ALIGN_EPI = false, bool SP2 = false>
; __device__ __forceinline__ void gemm_phase(PG8_LAS unsigned char* lds, const Gemm g, const Sched& S, const Epi& E, const int wid_in) {
;     ...
;         for (int t = 0; t < nt; t += 2) {
;     ...
;             PG8_LDA(At, 1, 1); PG8_STAGE(PG8_SB(1, 0), b3, voffB); PG8_STAGE(PG8_SB(1, 1), b3 + hstep, voffB); PG8_STAGE(PG8_SA(1, 0), a3, voffA);
;             PG8_WAIT_V(8); PG8_WAIT_L(0); PG8_BAR; PG8_MMA(1, 0, At, B0); PG8_MMA(1, 1, At, B1); PG8_BAR; PG8_SCHED;
	s_add_i32 s24, s26, s75
	v_lshl_add_u64 v[158:159], v[158:159], 0, s[8:9]
	s_mov_b32 m0, s24
	ds_read_b128 v[190:193], v183 offset:49152
	ds_read_b128 v[194:197], v183 offset:50176
	ds_read_b128 v[198:201], v183 offset:51200
	ds_read_b128 v[202:205], v183 offset:52224
	ds_read_b128 v[206:209], v183 offset:53248
	ds_read_b128 v[210:213], v183 offset:54272
	ds_read_b128 v[214:217], v183 offset:55296
	ds_read_b128 v[218:221], v183 offset:56320
	global_load_lds_dwordx4 v[158:159], off
	s_add_i32 m0, s24, 0x2000
	s_add_u32 s24, s44, 0x80080
	v_lshl_add_u64 v[158:159], v[180:181], 0, s[8:9]
	s_addc_u32 s25, s45, 0
	s_add_i32 s26, s27, s75
	global_load_lds_dwordx4 v[158:159], off
	v_lshl_add_u64 v[158:159], s[24:25], 0, v[130:131]
	s_mov_b32 m0, s26
	s_nop 0
	global_load_lds_dwordx4 v[158:159], off
	v_lshl_add_u64 v[158:159], s[24:25], 0, v[134:135]
	s_add_i32 m0, s26, 0x2000
	s_nop 0
	global_load_lds_dwordx4 v[158:159], off
	v_lshl_add_u64 v[158:159], v[222:223], 0, s[8:9]
	s_mov_b32 m0, s81
	s_nop 0
	global_load_lds_dwordx4 v[158:159], off
	v_lshl_add_u64 v[158:159], v[224:225], 0, s[8:9]
	s_mov_b32 m0, s82
	s_nop 0
	global_load_lds_dwordx4 v[158:159], off
	s_waitcnt vmcnt(8)
	s_waitcnt lgkmcnt(0)
	s_barrier
	s_setprio 1
	s_waitcnt lgkmcnt(0)
	v_mfma_f32_16x16x32_bf16 v[60:63], v[146:149], v[190:193], v[60:63]
	v_mfma_f32_16x16x32_bf16 v[56:59], v[154:157], v[190:193], v[56:59]
	v_mfma_f32_16x16x32_bf16 v[44:47], v[146:149], v[198:201], v[44:47]
	v_mfma_f32_16x16x32_bf16 v[40:43], v[154:157], v[198:201], v[40:43]
	v_mfma_f32_16x16x32_bf16 v[28:31], v[146:149], v[206:209], v[28:31]
	v_mfma_f32_16x16x32_bf16 v[24:27], v[154:157], v[206:209], v[24:27]
	v_mfma_f32_16x16x32_bf16 v[12:15], v[146:149], v[214:217], v[12:15]
	v_mfma_f32_16x16x32_bf16 v[8:11], v[154:157], v[214:217], v[8:11]
	v_mfma_f32_16x16x32_bf16 v[60:63], v[150:153], v[194:197], v[60:63]
	v_mfma_f32_16x16x32_bf16 v[56:59], v[164:167], v[194:197], v[56:59]
	v_mfma_f32_16x16x32_bf16 v[44:47], v[150:153], v[202:205], v[44:47]
	v_mfma_f32_16x16x32_bf16 v[40:43], v[164:167], v[202:205], v[40:43]
	v_mfma_f32_16x16x32_bf16 v[28:31], v[150:153], v[210:213], v[28:31]
	v_mfma_f32_16x16x32_bf16 v[24:27], v[164:167], v[210:213], v[24:27]
	v_mfma_f32_16x16x32_bf16 v[12:15], v[150:153], v[218:221], v[12:15]
	v_mfma_f32_16x16x32_bf16 v[8:11], v[164:167], v[218:221], v[8:11]
	s_setprio 0
	s_setprio 1
	v_mfma_f32_16x16x32_bf16 v[52:55], v[168:171], v[190:193], v[52:55]
	v_mfma_f32_16x16x32_bf16 v[48:51], v[176:179], v[190:193], v[48:51]
	v_mfma_f32_16x16x32_bf16 v[36:39], v[168:171], v[198:201], v[36:39]
	v_mfma_f32_16x16x32_bf16 v[32:35], v[176:179], v[198:201], v[32:35]
	v_mfma_f32_16x16x32_bf16 v[20:23], v[168:171], v[206:209], v[20:23]
	v_mfma_f32_16x16x32_bf16 v[16:19], v[176:179], v[206:209], v[16:19]
	v_mfma_f32_16x16x32_bf16 v[4:7], v[168:171], v[214:217], v[4:7]
	v_mfma_f32_16x16x32_bf16 v[0:3], v[176:179], v[214:217], v[0:3]
	v_mfma_f32_16x16x32_bf16 v[52:55], v[172:175], v[194:197], v[52:55]
	v_mfma_f32_16x16x32_bf16 v[48:51], v[186:189], v[194:197], v[48:51]
	v_mfma_f32_16x16x32_bf16 v[36:39], v[172:175], v[202:205], v[36:39]
	v_mfma_f32_16x16x32_bf16 v[32:35], v[186:189], v[202:205], v[32:35]
	v_mfma_f32_16x16x32_bf16 v[20:23], v[172:175], v[210:213], v[20:23]
	v_mfma_f32_16x16x32_bf16 v[16:19], v[186:189], v[210:213], v[16:19]
	v_mfma_f32_16x16x32_bf16 v[4:7], v[172:175], v[218:221], v[4:7]
	v_mfma_f32_16x16x32_bf16 v[0:3], v[186:189], v[218:221], v[0:3]
	s_setprio 0
	s_add_i32 s39, s39, 2
	s_add_u32 s42, s42, 0x100
	s_addc_u32 s43, s43, 0
	s_add_u32 s34, s34, 0x100
	s_addc_u32 s35, s35, 0
	s_cmp_gt_u32 s39, 29
	s_barrier
	s_cbranch_scc0 .LBB0_160
	s_and_b64 vcc, exec, s[60:61]
	s_movk_i32 s26, 0x2000
	s_cbranch_vccz .LBB0_163
	s_barrier

; #define PG8_STAGE(bufoff, gbase, voff) do { _Pragma("unroll") for (int _i = 0; _i < 2; ++_i) \
;         __builtin_amdgcn_global_load_lds((const unsigned*)((const char*)(gbase) + (voff)[_i]), (PG8_LAS unsigned*)(lds + (bufoff) + ldsw + _i * 8192), 16, 0, 0); } while (0)
; #define PG8_LDA(dst, b, h) do { _Pragma("unroll") for (int m = 0; m < 4; ++m) _Pragma("unroll") for (int k = 0; k < 2; ++k) dst[m][k] = *(const PG8_LAS bf16x8*)(lds + PG8_SA(b, h) + aoff + m * 2048 + k * 1024); } while (0)
; #define PG8_LDB(dst, b, h) do { _Pragma("unroll") for (int n = 0; n < 2; ++n) _Pragma("unroll") for (int k = 0; k < 2; ++k) dst[n][k] = *(const PG8_LAS bf16x8*)(lds + PG8_SB(b, h) + boff + n * 2048 + k * 1024); } while (0)
; #define PG8_MMA(ai, bj, At, Bt) do { __builtin_amdgcn_s_setprio(1); _Pragma("unroll") for (int m = 0; m < 4; ++m) _Pragma("unroll") for (int n = 0; n < 2; ++n) _Pragma("unroll") for (int k = 0; k < 2; ++k) \
;         acc[ai][bj][m][n] = __builtin_amdgcn_mfma_f32_16x16x32_bf16(Bt[n][k], At[m][k], acc[ai][bj][m][n], 0, 0, 0); __builtin_amdgcn_s_setprio(0); } while (0)
; #define PG8_WAIT_V(n) asm volatile("s_waitcnt vmcnt(" #n ")" ::: "memory")
; #define PG8_WAIT_L(n) asm volatile("s_waitcnt lgkmcnt(" #n ")" ::: "memory")
; #define PG8_BAR __builtin_amdgcn_s_barrier()
; template <class Epi, class Sched, bool ALIGN_EPI = false, bool SP2 = false>
; __device__ __forceinline__ void gemm_phase(PG8_LAS unsigned char* lds, const Gemm g, const Sched& S, const Epi& E, const int wid_in) {
;     ...
;         for (int t = 0; t < nt; t += 2) {
;             const bool last = (t == nt - 2);
;             const char* a1 = cA + (size_t)(t + 1) * kstep;
;             const char* a2 = last ? nA : cA + (size_t)(t + 2) * kstep; const char* b2 = last ? nB : cB + (size_t)(t + 2) * kstep;
;             const char* a3 = a2 + kstep; const char* b3 = b2 + kstep;
;             if (last && has_next) S.a_ready(nxt);
;             if constexpr (SP2) {
;             PG8_LDB(B0, 0, 0); PG8_LDB(B1, 0, 1); PG8_SCHED; PG8_LDA(At, 0, 0); PG8_STAGE(PG8_SA(1, 1), a1 + hstep, voffA);
;             PG8_WAIT_V(8); PG8_WAIT_L(0); PG8_BAR; PG8_MMA(0, 0, At, B0); PG8_MMA(0, 1, At, B1); PG8_BAR; PG8_SCHED;
;             PG8_LDA(At, 0, 1); PG8_STAGE(PG8_SB(0, 0), b2, voffB); PG8_STAGE(PG8_SB(0, 1), b2 + hstep, voffB); PG8_STAGE(PG8_SA(0, 0), a2, voffA);
.LBB0_527:
	s_add_u32 s24, s54, 0xfffc0080
	s_addc_u32 s25, s55, -1
	s_add_i32 s26, 0, 0x10000
	s_cmp_eq_u32 s71, 12
	s_cselect_b32 s59, s14, s25
	s_cselect_b32 s58, s15, s24
	v_add_u32_e32 v142, s26, v145
	s_cselect_b32 s57, s45, s70
	s_cselect_b32 s56, s47, s69
	s_add_i32 s27, 0, 0x14000
	ds_read_b128 v[138:141], v142
	ds_read_b128 v[148:151], v142 offset:1024
	ds_read_b128 v[152:155], v142 offset:2048
	ds_read_b128 v[156:159], v142 offset:3072
	v_add_u32_e32 v142, s27, v145
	ds_read_b128 v[162:165], v142
	ds_read_b128 v[166:169], v142 offset:1024
	ds_read_b128 v[170:173], v142 offset:2048
	ds_read_b128 v[174:177], v142 offset:3072
	v_lshl_add_u64 v[142:143], s[54:55], 0, v[134:135]
	s_add_i32 m0, s53, 0xc000
	ds_read_b128 v[178:181], v147
	ds_read_b128 v[182:185], v147 offset:1024
	ds_read_b128 v[186:189], v147 offset:2048
	ds_read_b128 v[190:193], v147 offset:3072
	ds_read_b128 v[194:197], v147 offset:4096
	ds_read_b128 v[198:201], v147 offset:5120
	ds_read_b128 v[202:205], v147 offset:6144
	ds_read_b128 v[206:209], v147 offset:7168
	global_load_lds_dwordx4 v[142:143], off
	v_lshl_add_u64 v[142:143], s[54:55], 0, v[136:137]
	s_add_i32 m0, s53, 0xe000
	s_nop 0
	global_load_lds_dwordx4 v[142:143], off
	s_waitcnt vmcnt(8)
	s_waitcnt lgkmcnt(0)
	s_barrier
	s_setprio 1
	s_waitcnt lgkmcnt(0)
	v_mfma_f32_16x16x32_bf16 v[124:127], v[138:141], v[178:181], v[124:127]
	v_mfma_f32_16x16x32_bf16 v[120:123], v[152:155], v[178:181], v[120:123]
	v_mfma_f32_16x16x32_bf16 v[108:111], v[138:141], v[186:189], v[108:111]
	v_mfma_f32_16x16x32_bf16 v[104:107], v[152:155], v[186:189], v[104:107]
	v_mfma_f32_16x16x32_bf16 v[92:95], v[138:141], v[194:197], v[92:95]
	v_mfma_f32_16x16x32_bf16 v[88:91], v[152:155], v[194:197], v[88:91]
	v_mfma_f32_16x16x32_bf16 v[76:79], v[138:141], v[202:205], v[76:79]
	v_mfma_f32_16x16x32_bf16 v[72:75], v[152:155], v[202:205], v[72:75]
	v_mfma_f32_16x16x32_bf16 v[124:127], v[148:151], v[182:185], v[124:127]
	v_mfma_f32_16x16x32_bf16 v[120:123], v[156:159], v[182:185], v[120:123]
	v_mfma_f32_16x16x32_bf16 v[108:111], v[148:151], v[190:193], v[108:111]
	v_mfma_f32_16x16x32_bf16 v[104:107], v[156:159], v[190:193], v[104:107]
	v_mfma_f32_16x16x32_bf16 v[92:95], v[148:151], v[198:201], v[92:95]
	v_mfma_f32_16x16x32_bf16 v[88:91], v[156:159], v[198:201], v[88:91]
	v_mfma_f32_16x16x32_bf16 v[76:79], v[148:151], v[206:209], v[76:79]
	v_mfma_f32_16x16x32_bf16 v[72:75], v[156:159], v[206:209], v[72:75]
	s_setprio 0
	s_setprio 1
	v_mfma_f32_16x16x32_bf16 v[116:119], v[162:165], v[178:181], v[116:119]
	v_mfma_f32_16x16x32_bf16 v[112:115], v[170:173], v[178:181], v[112:115]
	v_mfma_f32_16x16x32_bf16 v[100:103], v[162:165], v[186:189], v[100:103]
	v_mfma_f32_16x16x32_bf16 v[96:99], v[170:173], v[186:189], v[96:99]
	v_mfma_f32_16x16x32_bf16 v[84:87], v[162:165], v[194:197], v[84:87]
	v_mfma_f32_16x16x32_bf16 v[80:83], v[170:173], v[194:197], v[80:83]
	v_mfma_f32_16x16x32_bf16 v[68:71], v[162:165], v[202:205], v[68:71]
	v_mfma_f32_16x16x32_bf16 v[64:67], v[170:173], v[202:205], v[64:67]
	v_mfma_f32_16x16x32_bf16 v[116:119], v[166:169], v[182:185], v[116:119]
	v_mfma_f32_16x16x32_bf16 v[112:115], v[174:177], v[182:185], v[112:115]
	v_mfma_f32_16x16x32_bf16 v[100:103], v[166:169], v[190:193], v[100:103]
	v_mfma_f32_16x16x32_bf16 v[96:99], v[174:177], v[190:193], v[96:99]
	v_mfma_f32_16x16x32_bf16 v[84:87], v[166:169], v[198:201], v[84:87]
	v_mfma_f32_16x16x32_bf16 v[80:83], v[174:177], v[198:201], v[80:83]
	v_mfma_f32_16x16x32_bf16 v[68:71], v[166:169], v[206:209], v[68:71]
	v_mfma_f32_16x16x32_bf16 v[64:67], v[174:177], v[206:209], v[64:67]
	s_setprio 0
	s_barrier
	s_add_i32 s24, s26, s62
	v_lshl_add_u64 v[142:143], s[56:57], 0, v[160:161]
	s_mov_b32 m0, s24
	ds_read_b128 v[178:181], v147 offset:16384
	ds_read_b128 v[182:185], v147 offset:17408
	ds_read_b128 v[186:189], v147 offset:18432
	ds_read_b128 v[190:193], v147 offset:19456
	ds_read_b128 v[194:197], v147 offset:20480
	ds_read_b128 v[198:201], v147 offset:21504
	ds_read_b128 v[202:205], v147 offset:22528
	ds_read_b128 v[206:209], v147 offset:23552
	global_load_lds_dwordx4 v[142:143], off
	s_add_i32 m0, s24, 0x2000
	s_add_u32 s24, s56, 0x40000
	v_lshl_add_u64 v[210:211], s[56:57], 0, v[132:133]
	s_addc_u32 s25, s57, 0
	s_add_i32 s26, s27, s62
	global_load_lds_dwordx4 v[210:211], off
	v_lshl_add_u64 v[212:213], s[24:25], 0, v[160:161]
	s_mov_b32 m0, s26
	v_lshl_add_u64 v[214:215], s[58:59], 0, v[130:131]
	global_load_lds_dwordx4 v[212:213], off
	v_lshl_add_u64 v[212:213], s[24:25], 0, v[132:133]
	s_add_i32 m0, s26, 0x2000
	s_nop 0
	global_load_lds_dwordx4 v[212:213], off
	v_lshl_add_u64 v[212:213], s[58:59], 0, v[128:129]
	s_mov_b32 m0, s53
	s_nop 0
	global_load_lds_dwordx4 v[212:213], off
	s_mov_b32 m0, s63
	s_nop 0
	global_load_lds_dwordx4 v[214:215], off
	s_waitcnt vmcnt(8)
	s_waitcnt lgkmcnt(0)
	s_barrier
; #define PG8_STAGE(bufoff, gbase, voff) do { _Pragma("unroll") for (int _i = 0; _i < 2; ++_i) \
;         __builtin_amdgcn_global_load_lds((const unsigned*)((const char*)(gbase) + (voff)[_i]), (PG8_LAS unsigned*)(lds + (bufoff) + ldsw + _i * 8192), 16, 0, 0); } while (0)
; #define PG8_LDA(dst, b, h) do { _Pragma("unroll") for (int m = 0; m < 4; ++m) _Pragma("unroll") for (int k = 0; k < 2; ++k) dst[m][k] = *(const PG8_LAS bf16x8*)(lds + PG8_SA(b, h) + aoff + m * 2048 + k * 1024); } while (0)
; #define PG8_LDB(dst, b, h) do { _Pragma("unroll") for (int n = 0; n < 2; ++n) _Pragma("unroll") for (int k = 0; k < 2; ++k) dst[n][k] = *(const PG8_LAS bf16x8*)(lds + PG8_SB(b, h) + boff + n * 2048 + k * 1024); } while (0)
; #define PG8_MMA(ai, bj, At, Bt) do { __builtin_amdgcn_s_setprio(1); _Pragma("unroll") for (int m = 0; m < 4; ++m) _Pragma("unroll") for (int n = 0; n < 2; ++n) _Pragma("unroll") for (int k = 0; k < 2; ++k) \
;         acc[ai][bj][m][n] = __builtin_amdgcn_mfma_f32_16x16x32_bf16(Bt[n][k], At[m][k], acc[ai][bj][m][n], 0, 0, 0); __builtin_amdgcn_s_setprio(0); } while (0)
; #define PG8_WAIT_V(n) asm volatile("s_waitcnt vmcnt(" #n ")" ::: "memory")
; #define PG8_WAIT_L(n) asm volatile("s_waitcnt lgkmcnt(" #n ")" ::: "memory")
; #define PG8_BAR __builtin_amdgcn_s_barrier()
; #define PG8_SCHED __builtin_amdgcn_sched_barrier(0)
; template <class Epi, class Sched, bool ALIGN_EPI = false, bool SP2 = false>
; __device__ __forceinline__ void gemm_phase(PG8_LAS unsigned char* lds, const Gemm g, const Sched& S, const Epi& E, const int wid_in) {
;     ...
;             PG8_WAIT_V(8); PG8_WAIT_L(0); PG8_BAR; PG8_MMA(1, 0, At, B0); PG8_MMA(1, 1, At, B1); PG8_BAR; PG8_SCHED;
;             PG8_LDB(B0, 1, 0); PG8_LDB(B1, 1, 1); PG8_SCHED; PG8_LDA(At, 1, 0); PG8_STAGE(PG8_SA(0, 1), a2 + hstep, voffA);
;             PG8_WAIT_V(8); PG8_WAIT_L(0); PG8_BAR; PG8_MMA(0, 0, At, B0); PG8_MMA(0, 1, At, B1); PG8_BAR; PG8_SCHED;
	s_setprio 1
	s_waitcnt lgkmcnt(0)
	v_mfma_f32_16x16x32_bf16 v[60:63], v[138:141], v[178:181], v[60:63]
	v_mfma_f32_16x16x32_bf16 v[56:59], v[152:155], v[178:181], v[56:59]
	v_mfma_f32_16x16x32_bf16 v[44:47], v[138:141], v[186:189], v[44:47]
	v_mfma_f32_16x16x32_bf16 v[40:43], v[152:155], v[186:189], v[40:43]
	v_mfma_f32_16x16x32_bf16 v[28:31], v[138:141], v[194:197], v[28:31]
	v_mfma_f32_16x16x32_bf16 v[24:27], v[152:155], v[194:197], v[24:27]
	v_mfma_f32_16x16x32_bf16 v[12:15], v[138:141], v[202:205], v[12:15]
	v_mfma_f32_16x16x32_bf16 v[8:11], v[152:155], v[202:205], v[8:11]
	v_mfma_f32_16x16x32_bf16 v[60:63], v[148:151], v[182:185], v[60:63]
	v_mfma_f32_16x16x32_bf16 v[56:59], v[156:159], v[182:185], v[56:59]
	v_mfma_f32_16x16x32_bf16 v[44:47], v[148:151], v[190:193], v[44:47]
	v_mfma_f32_16x16x32_bf16 v[40:43], v[156:159], v[190:193], v[40:43]
	v_mfma_f32_16x16x32_bf16 v[28:31], v[148:151], v[198:201], v[28:31]
	v_mfma_f32_16x16x32_bf16 v[24:27], v[156:159], v[198:201], v[24:27]
	v_mfma_f32_16x16x32_bf16 v[12:15], v[148:151], v[206:209], v[12:15]
	v_mfma_f32_16x16x32_bf16 v[8:11], v[156:159], v[206:209], v[8:11]
	s_setprio 0
	s_setprio 1
	v_mfma_f32_16x16x32_bf16 v[52:55], v[162:165], v[178:181], v[52:55]
	v_mfma_f32_16x16x32_bf16 v[48:51], v[170:173], v[178:181], v[48:51]
	v_mfma_f32_16x16x32_bf16 v[36:39], v[162:165], v[186:189], v[36:39]
	v_mfma_f32_16x16x32_bf16 v[32:35], v[170:173], v[186:189], v[32:35]
	v_mfma_f32_16x16x32_bf16 v[20:23], v[162:165], v[194:197], v[20:23]
	v_mfma_f32_16x16x32_bf16 v[16:19], v[170:173], v[194:197], v[16:19]
	v_mfma_f32_16x16x32_bf16 v[4:7], v[162:165], v[202:205], v[4:7]
	v_mfma_f32_16x16x32_bf16 v[0:3], v[170:173], v[202:205], v[0:3]
	v_mfma_f32_16x16x32_bf16 v[52:55], v[166:169], v[182:185], v[52:55]
	v_mfma_f32_16x16x32_bf16 v[48:51], v[174:177], v[182:185], v[48:51]
	v_mfma_f32_16x16x32_bf16 v[36:39], v[166:169], v[190:193], v[36:39]
	v_mfma_f32_16x16x32_bf16 v[32:35], v[174:177], v[190:193], v[32:35]
	v_mfma_f32_16x16x32_bf16 v[20:23], v[166:169], v[198:201], v[20:23]
	v_mfma_f32_16x16x32_bf16 v[16:19], v[174:177], v[198:201], v[16:19]
	v_mfma_f32_16x16x32_bf16 v[4:7], v[166:169], v[206:209], v[4:7]
	v_mfma_f32_16x16x32_bf16 v[0:3], v[174:177], v[206:209], v[0:3]
	s_setprio 0
	s_barrier
	s_add_i32 s26, 0, 0x18000
	s_add_i32 s27, 0, 0x1c000
	v_add_u32_e32 v156, s26, v145
	v_add_u32_e32 v174, s27, v145
	ds_read_b128 v[138:141], v156
	ds_read_b128 v[148:151], v156 offset:1024
	ds_read_b128 v[152:155], v156 offset:2048
	ds_read_b128 v[156:159], v156 offset:3072
	ds_read_b128 v[162:165], v174
	ds_read_b128 v[166:169], v174 offset:1024
	ds_read_b128 v[170:173], v174 offset:2048
	ds_read_b128 v[174:177], v174 offset:3072
	s_add_u32 s24, s58, 0x40000
	s_addc_u32 s25, s59, 0
	s_mov_b32 m0, s64
	v_lshl_add_u64 v[216:217], s[24:25], 0, v[128:129]
	ds_read_b128 v[178:181], v147 offset:32768
	ds_read_b128 v[182:185], v147 offset:33792
	ds_read_b128 v[186:189], v147 offset:34816
	ds_read_b128 v[190:193], v147 offset:35840
	ds_read_b128 v[194:197], v147 offset:36864
	ds_read_b128 v[198:201], v147 offset:37888
	ds_read_b128 v[202:205], v147 offset:38912
	ds_read_b128 v[206:209], v147 offset:39936
	global_load_lds_dwordx4 v[216:217], off
	v_lshl_add_u64 v[216:217], s[24:25], 0, v[130:131]
	s_mov_b32 m0, s65
	s_nop 0
	global_load_lds_dwordx4 v[216:217], off
	s_waitcnt vmcnt(8)
	s_waitcnt lgkmcnt(0)
	s_barrier
	s_setprio 1
	s_waitcnt lgkmcnt(0)
	v_mfma_f32_16x16x32_bf16 v[124:127], v[138:141], v[178:181], v[124:127]
	v_mfma_f32_16x16x32_bf16 v[120:123], v[152:155], v[178:181], v[120:123]
	v_mfma_f32_16x16x32_bf16 v[108:111], v[138:141], v[186:189], v[108:111]
	v_mfma_f32_16x16x32_bf16 v[104:107], v[152:155], v[186:189], v[104:107]
	v_mfma_f32_16x16x32_bf16 v[92:95], v[138:141], v[194:197], v[92:95]
	v_mfma_f32_16x16x32_bf16 v[88:91], v[152:155], v[194:197], v[88:91]
	v_mfma_f32_16x16x32_bf16 v[76:79], v[138:141], v[202:205], v[76:79]
	v_mfma_f32_16x16x32_bf16 v[72:75], v[152:155], v[202:205], v[72:75]
	v_mfma_f32_16x16x32_bf16 v[124:127], v[148:151], v[182:185], v[124:127]
	v_mfma_f32_16x16x32_bf16 v[120:123], v[156:159], v[182:185], v[120:123]
	v_mfma_f32_16x16x32_bf16 v[108:111], v[148:151], v[190:193], v[108:111]
	v_mfma_f32_16x16x32_bf16 v[104:107], v[156:159], v[190:193], v[104:107]
	v_mfma_f32_16x16x32_bf16 v[92:95], v[148:151], v[198:201], v[92:95]
	v_mfma_f32_16x16x32_bf16 v[88:91], v[156:159], v[198:201], v[88:91]
	v_mfma_f32_16x16x32_bf16 v[76:79], v[148:151], v[206:209], v[76:79]
	v_mfma_f32_16x16x32_bf16 v[72:75], v[156:159], v[206:209], v[72:75]
	s_setprio 0
	s_setprio 1
	v_mfma_f32_16x16x32_bf16 v[116:119], v[162:165], v[178:181], v[116:119]
	v_mfma_f32_16x16x32_bf16 v[112:115], v[170:173], v[178:181], v[112:115]
	v_mfma_f32_16x16x32_bf16 v[100:103], v[162:165], v[186:189], v[100:103]
	v_mfma_f32_16x16x32_bf16 v[96:99], v[170:173], v[186:189], v[96:99]
	v_mfma_f32_16x16x32_bf16 v[84:87], v[162:165], v[194:197], v[84:87]
	v_mfma_f32_16x16x32_bf16 v[80:83], v[170:173], v[194:197], v[80:83]
	v_mfma_f32_16x16x32_bf16 v[68:71], v[162:165], v[202:205], v[68:71]
	v_mfma_f32_16x16x32_bf16 v[64:67], v[170:173], v[202:205], v[64:67]
	v_mfma_f32_16x16x32_bf16 v[116:119], v[166:169], v[182:185], v[116:119]
	v_mfma_f32_16x16x32_bf16 v[112:115], v[174:177], v[182:185], v[112:115]
	v_mfma_f32_16x16x32_bf16 v[100:103], v[166:169], v[190:193], v[100:103]
	v_mfma_f32_16x16x32_bf16 v[96:99], v[174:177], v[190:193], v[96:99]
	v_mfma_f32_16x16x32_bf16 v[84:87], v[166:169], v[198:201], v[84:87]
	v_mfma_f32_16x16x32_bf16 v[80:83], v[174:177], v[198:201], v[80:83]
	v_mfma_f32_16x16x32_bf16 v[68:71], v[166:169], v[206:209], v[68:71]
	v_mfma_f32_16x16x32_bf16 v[64:67], v[174:177], v[206:209], v[64:67]
	s_setprio 0
	s_barrier
; #define PG8_STAGE(bufoff, gbase, voff) do { _Pragma("unroll") for (int _i = 0; _i < 2; ++_i) \
;         __builtin_amdgcn_global_load_lds((const unsigned*)((const char*)(gbase) + (voff)[_i]), (PG8_LAS unsigned*)(lds + (bufoff) + ldsw + _i * 8192), 16, 0, 0); } while (0)
; #define PG8_LDA(dst, b, h) do { _Pragma("unroll") for (int m = 0; m < 4; ++m) _Pragma("unroll") for (int k = 0; k < 2; ++k) dst[m][k] = *(const PG8_LAS bf16x8*)(lds + PG8_SA(b, h) + aoff + m * 2048 + k * 1024); } while (0)
; #define PG8_MMA(ai, bj, At, Bt) do { __builtin_amdgcn_s_setprio(1); _Pragma("unroll") for (int m = 0; m < 4; ++m) _Pragma("unroll") for (int n = 0; n < 2; ++n) _Pragma("unroll") for (int k = 0; k < 2; ++k) \
;         acc[ai][bj][m][n] = __builtin_amdgcn_mfma_f32_16x16x32_bf16(Bt[n][k], At[m][k], acc[ai][bj][m][n], 0, 0, 0); __builtin_amdgcn_s_setprio(0); } while (0)
; #define PG8_WAIT_V(n) asm volatile("s_waitcnt vmcnt(" #n ")" ::: "memory")
; #define PG8_WAIT_L(n) asm volatile("s_waitcnt lgkmcnt(" #n ")" ::: "memory")
; #define PG8_BAR __builtin_amdgcn_s_barrier()
; #define PG8_SCHED __builtin_amdgcn_sched_barrier(0)
; template <class Epi, class Sched, bool ALIGN_EPI = false, bool SP2 = false>
; __device__ __forceinline__ void gemm_phase(PG8_LAS unsigned char* lds, const Gemm g, const Sched& S, const Epi& E, const int wid_in) {
;     ...
;         for (int t = 0; t < nt; t += 2) {
;             const bool last = (t == nt - 2);
;     ...
;             PG8_WAIT_V(8); PG8_WAIT_L(0); PG8_BAR; PG8_MMA(0, 0, At, B0); PG8_MMA(0, 1, At, B1); PG8_BAR; PG8_SCHED;
;             PG8_LDA(At, 1, 1); PG8_STAGE(PG8_SB(1, 0), b3, voffB); PG8_STAGE(PG8_SB(1, 1), b3 + hstep, voffB); PG8_STAGE(PG8_SA(1, 0), a3, voffA);
;             PG8_WAIT_V(8); PG8_WAIT_L(0); PG8_BAR; PG8_MMA(1, 0, At, B0); PG8_MMA(1, 1, At, B1); PG8_BAR; PG8_SCHED;
	s_add_i32 s24, s26, s62
	v_lshl_add_u64 v[142:143], v[142:143], 0, s[8:9]
	s_mov_b32 m0, s24
	ds_read_b128 v[178:181], v147 offset:49152
	ds_read_b128 v[182:185], v147 offset:50176
	ds_read_b128 v[186:189], v147 offset:51200
	ds_read_b128 v[190:193], v147 offset:52224
	ds_read_b128 v[194:197], v147 offset:53248
	ds_read_b128 v[198:201], v147 offset:54272
	ds_read_b128 v[202:205], v147 offset:55296
	ds_read_b128 v[206:209], v147 offset:56320
	global_load_lds_dwordx4 v[142:143], off
	s_add_i32 m0, s24, 0x2000
	s_add_u32 s24, s56, 0x40080
	v_lshl_add_u64 v[142:143], v[210:211], 0, s[8:9]
	s_addc_u32 s25, s57, 0
	s_add_i32 s26, s27, s62
	global_load_lds_dwordx4 v[142:143], off
	v_lshl_add_u64 v[142:143], s[24:25], 0, v[160:161]
	s_mov_b32 m0, s26
	s_nop 0
	global_load_lds_dwordx4 v[142:143], off
	v_lshl_add_u64 v[142:143], s[24:25], 0, v[132:133]
	s_add_i32 m0, s26, 0x2000
	s_nop 0
	global_load_lds_dwordx4 v[142:143], off
	v_lshl_add_u64 v[142:143], v[212:213], 0, s[8:9]
	s_mov_b32 m0, s66
	s_nop 0
	global_load_lds_dwordx4 v[142:143], off
	v_lshl_add_u64 v[142:143], v[214:215], 0, s[8:9]
	s_mov_b32 m0, s67
	s_nop 0
	global_load_lds_dwordx4 v[142:143], off
	s_waitcnt vmcnt(8)
	s_waitcnt lgkmcnt(0)
	s_barrier
	s_setprio 1
	s_waitcnt lgkmcnt(0)
	v_mfma_f32_16x16x32_bf16 v[60:63], v[138:141], v[178:181], v[60:63]
	v_mfma_f32_16x16x32_bf16 v[56:59], v[152:155], v[178:181], v[56:59]
	v_mfma_f32_16x16x32_bf16 v[44:47], v[138:141], v[186:189], v[44:47]
	v_mfma_f32_16x16x32_bf16 v[40:43], v[152:155], v[186:189], v[40:43]
	v_mfma_f32_16x16x32_bf16 v[28:31], v[138:141], v[194:197], v[28:31]
	v_mfma_f32_16x16x32_bf16 v[24:27], v[152:155], v[194:197], v[24:27]
	v_mfma_f32_16x16x32_bf16 v[12:15], v[138:141], v[202:205], v[12:15]
	v_mfma_f32_16x16x32_bf16 v[8:11], v[152:155], v[202:205], v[8:11]
	v_mfma_f32_16x16x32_bf16 v[60:63], v[148:151], v[182:185], v[60:63]
	v_mfma_f32_16x16x32_bf16 v[56:59], v[156:159], v[182:185], v[56:59]
	v_mfma_f32_16x16x32_bf16 v[44:47], v[148:151], v[190:193], v[44:47]
	v_mfma_f32_16x16x32_bf16 v[40:43], v[156:159], v[190:193], v[40:43]
	v_mfma_f32_16x16x32_bf16 v[28:31], v[148:151], v[198:201], v[28:31]
	v_mfma_f32_16x16x32_bf16 v[24:27], v[156:159], v[198:201], v[24:27]
	v_mfma_f32_16x16x32_bf16 v[12:15], v[148:151], v[206:209], v[12:15]
	v_mfma_f32_16x16x32_bf16 v[8:11], v[156:159], v[206:209], v[8:11]
	s_setprio 0
	s_setprio 1
	v_mfma_f32_16x16x32_bf16 v[52:55], v[162:165], v[178:181], v[52:55]
	v_mfma_f32_16x16x32_bf16 v[48:51], v[170:173], v[178:181], v[48:51]
	v_mfma_f32_16x16x32_bf16 v[36:39], v[162:165], v[186:189], v[36:39]
	v_mfma_f32_16x16x32_bf16 v[32:35], v[170:173], v[186:189], v[32:35]
	v_mfma_f32_16x16x32_bf16 v[20:23], v[162:165], v[194:197], v[20:23]
	v_mfma_f32_16x16x32_bf16 v[16:19], v[170:173], v[194:197], v[16:19]
	v_mfma_f32_16x16x32_bf16 v[4:7], v[162:165], v[202:205], v[4:7]
	v_mfma_f32_16x16x32_bf16 v[0:3], v[170:173], v[202:205], v[0:3]
	v_mfma_f32_16x16x32_bf16 v[52:55], v[166:169], v[182:185], v[52:55]
	v_mfma_f32_16x16x32_bf16 v[48:51], v[174:177], v[182:185], v[48:51]
	v_mfma_f32_16x16x32_bf16 v[36:39], v[166:169], v[190:193], v[36:39]
	v_mfma_f32_16x16x32_bf16 v[32:35], v[174:177], v[190:193], v[32:35]
	v_mfma_f32_16x16x32_bf16 v[20:23], v[166:169], v[198:201], v[20:23]
	v_mfma_f32_16x16x32_bf16 v[16:19], v[174:177], v[198:201], v[16:19]
	v_mfma_f32_16x16x32_bf16 v[4:7], v[166:169], v[206:209], v[4:7]
	v_mfma_f32_16x16x32_bf16 v[0:3], v[174:177], v[206:209], v[0:3]
	s_setprio 0
	s_add_i32 s71, s71, 2
	s_add_u32 s54, s54, 0x100
	s_addc_u32 s55, s55, 0
	s_add_u32 s69, s69, 0x100
	s_addc_u32 s70, s70, 0
	s_cmp_gt_u32 s71, 13
	s_barrier
	s_cbranch_scc0 .LBB0_527
	s_and_b64 vcc, exec, s[42:43]
	s_cbranch_vccz .LBB0_530
	s_barrier

; #define PG8_STAGE(bufoff, gbase, voff) do { _Pragma("unroll") for (int _i = 0; _i < 2; ++_i) \
;         __builtin_amdgcn_global_load_lds((const unsigned*)((const char*)(gbase) + (voff)[_i]), (PG8_LAS unsigned*)(lds + (bufoff) + ldsw + _i * 8192), 16, 0, 0); } while (0)
; #define PG8_LDA(dst, b, h) do { _Pragma("unroll") for (int m = 0; m < 4; ++m) _Pragma("unroll") for (int k = 0; k < 2; ++k) dst[m][k] = *(const PG8_LAS bf16x8*)(lds + PG8_SA(b, h) + aoff + m * 2048 + k * 1024); } while (0)
; #define PG8_LDB(dst, b, h) do { _Pragma("unroll") for (int n = 0; n < 2; ++n) _Pragma("unroll") for (int k = 0; k < 2; ++k) dst[n][k] = *(const PG8_LAS bf16x8*)(lds + PG8_SB(b, h) + boff + n * 2048 + k * 1024); } while (0)
; #define PG8_MMA(ai, bj, At, Bt) do { __builtin_amdgcn_s_setprio(1); _Pragma("unroll") for (int m = 0; m < 4; ++m) _Pragma("unroll") for (int n = 0; n < 2; ++n) _Pragma("unroll") for (int k = 0; k < 2; ++k) \
;         acc[ai][bj][m][n] = __builtin_amdgcn_mfma_f32_16x16x32_bf16(Bt[n][k], At[m][k], acc[ai][bj][m][n], 0, 0, 0); __builtin_amdgcn_s_setprio(0); } while (0)
; #define PG8_WAIT_V(n) asm volatile("s_waitcnt vmcnt(" #n ")" ::: "memory")
; #define PG8_WAIT_L(n) asm volatile("s_waitcnt lgkmcnt(" #n ")" ::: "memory")
; #define PG8_BAR __builtin_amdgcn_s_barrier()
; template <class Epi, class Sched, bool ALIGN_EPI = false, bool SP2 = false>
; __device__ __forceinline__ void gemm_phase(PG8_LAS unsigned char* lds, const Gemm g, const Sched& S, const Epi& E, const int wid_in) {
;     ...
;         for (int t = 0; t < nt; t += 2) {
;             const bool last = (t == nt - 2);
;             const char* a1 = cA + (size_t)(t + 1) * kstep;
;             const char* a2 = last ? nA : cA + (size_t)(t + 2) * kstep; const char* b2 = last ? nB : cB + (size_t)(t + 2) * kstep;
;             const char* a3 = a2 + kstep; const char* b3 = b2 + kstep;
;             if (last && has_next) S.a_ready(nxt);
;             if constexpr (SP2) {
;             PG8_LDB(B0, 0, 0); PG8_LDB(B1, 0, 1); PG8_SCHED; PG8_LDA(At, 0, 0); PG8_STAGE(PG8_SA(1, 1), a1 + hstep, voffA);
;             PG8_WAIT_V(8); PG8_WAIT_L(0); PG8_BAR; PG8_MMA(0, 0, At, B0); PG8_MMA(0, 1, At, B1); PG8_BAR; PG8_SCHED;
;             PG8_LDA(At, 0, 1); PG8_STAGE(PG8_SB(0, 0), b2, voffB); PG8_STAGE(PG8_SB(0, 1), b2 + hstep, voffB); PG8_STAGE(PG8_SA(0, 0), a2, voffA);
.LBB0_674:
	s_add_u32 s24, s58, 0xfff80080
	s_addc_u32 s25, s59, -1
	s_add_i32 s26, 0, 0x10000
	s_cmp_eq_u32 s73, 28
	s_cselect_b32 s63, s14, s25
	s_cselect_b32 s62, s15, s24
	s_cselect_b32 s61, s49, s72
	s_cselect_b32 s60, s51, s71
	s_add_i32 s27, 0, 0x14000
	v_add_u32_e32 v154, s26, v143
	v_add_u32_e32 v158, s27, v143
	ds_read_b128 v[138:141], v154
	ds_read_b128 v[146:149], v154 offset:1024
	ds_read_b128 v[150:153], v154 offset:2048
	ds_read_b128 v[154:157], v154 offset:3072
	ds_read_b128 v[162:165], v158
	ds_read_b128 v[166:169], v158 offset:1024
	ds_read_b128 v[170:173], v158 offset:2048
	ds_read_b128 v[174:177], v158 offset:3072
	v_lshl_add_u64 v[158:159], s[58:59], 0, v[134:135]
	s_add_i32 m0, s57, 0xc000
	ds_read_b128 v[178:181], v145
	ds_read_b128 v[182:185], v145 offset:1024
	ds_read_b128 v[186:189], v145 offset:2048
	ds_read_b128 v[190:193], v145 offset:3072
	ds_read_b128 v[194:197], v145 offset:4096
	ds_read_b128 v[198:201], v145 offset:5120
	ds_read_b128 v[202:205], v145 offset:6144
	ds_read_b128 v[206:209], v145 offset:7168
	global_load_lds_dwordx4 v[158:159], off
	v_lshl_add_u64 v[158:159], s[58:59], 0, v[136:137]
	s_add_i32 m0, s57, 0xe000
	s_nop 0
	global_load_lds_dwordx4 v[158:159], off
	s_waitcnt vmcnt(8)
	s_waitcnt lgkmcnt(0)
	s_barrier
	s_setprio 1
	s_waitcnt lgkmcnt(0)
	v_mfma_f32_16x16x32_bf16 v[124:127], v[138:141], v[178:181], v[124:127]
	v_mfma_f32_16x16x32_bf16 v[120:123], v[150:153], v[178:181], v[120:123]
	v_mfma_f32_16x16x32_bf16 v[116:119], v[138:141], v[186:189], v[116:119]
	v_mfma_f32_16x16x32_bf16 v[108:111], v[150:153], v[186:189], v[108:111]
	v_mfma_f32_16x16x32_bf16 v[100:103], v[138:141], v[194:197], v[100:103]
	v_mfma_f32_16x16x32_bf16 v[92:95], v[150:153], v[194:197], v[92:95]
	v_mfma_f32_16x16x32_bf16 v[84:87], v[138:141], v[202:205], v[84:87]
	v_mfma_f32_16x16x32_bf16 v[76:79], v[150:153], v[202:205], v[76:79]
	v_mfma_f32_16x16x32_bf16 v[124:127], v[146:149], v[182:185], v[124:127]
	v_mfma_f32_16x16x32_bf16 v[120:123], v[154:157], v[182:185], v[120:123]
	v_mfma_f32_16x16x32_bf16 v[116:119], v[146:149], v[190:193], v[116:119]
	v_mfma_f32_16x16x32_bf16 v[108:111], v[154:157], v[190:193], v[108:111]
	v_mfma_f32_16x16x32_bf16 v[100:103], v[146:149], v[198:201], v[100:103]
	v_mfma_f32_16x16x32_bf16 v[92:95], v[154:157], v[198:201], v[92:95]
	v_mfma_f32_16x16x32_bf16 v[84:87], v[146:149], v[206:209], v[84:87]
	v_mfma_f32_16x16x32_bf16 v[76:79], v[154:157], v[206:209], v[76:79]
	s_setprio 0
	s_setprio 1
	v_mfma_f32_16x16x32_bf16 v[112:115], v[162:165], v[178:181], v[112:115]
	v_mfma_f32_16x16x32_bf16 v[104:107], v[170:173], v[178:181], v[104:107]
	v_mfma_f32_16x16x32_bf16 v[96:99], v[162:165], v[186:189], v[96:99]
	v_mfma_f32_16x16x32_bf16 v[88:91], v[170:173], v[186:189], v[88:91]
	v_mfma_f32_16x16x32_bf16 v[80:83], v[162:165], v[194:197], v[80:83]
	v_mfma_f32_16x16x32_bf16 v[72:75], v[170:173], v[194:197], v[72:75]
	v_mfma_f32_16x16x32_bf16 v[68:71], v[162:165], v[202:205], v[68:71]
	v_mfma_f32_16x16x32_bf16 v[64:67], v[170:173], v[202:205], v[64:67]
	v_mfma_f32_16x16x32_bf16 v[112:115], v[166:169], v[182:185], v[112:115]
	v_mfma_f32_16x16x32_bf16 v[104:107], v[174:177], v[182:185], v[104:107]
	v_mfma_f32_16x16x32_bf16 v[96:99], v[166:169], v[190:193], v[96:99]
	v_mfma_f32_16x16x32_bf16 v[88:91], v[174:177], v[190:193], v[88:91]
	v_mfma_f32_16x16x32_bf16 v[80:83], v[166:169], v[198:201], v[80:83]
	v_mfma_f32_16x16x32_bf16 v[72:75], v[174:177], v[198:201], v[72:75]
	v_mfma_f32_16x16x32_bf16 v[68:71], v[166:169], v[206:209], v[68:71]
	v_mfma_f32_16x16x32_bf16 v[64:67], v[174:177], v[206:209], v[64:67]
	s_setprio 0
	s_barrier
	s_add_i32 s24, s26, s35
	v_lshl_add_u64 v[158:159], s[60:61], 0, v[160:161]
	s_mov_b32 m0, s24
	ds_read_b128 v[178:181], v145 offset:16384
	ds_read_b128 v[182:185], v145 offset:17408
	ds_read_b128 v[186:189], v145 offset:18432
	ds_read_b128 v[190:193], v145 offset:19456
	ds_read_b128 v[194:197], v145 offset:20480
	ds_read_b128 v[198:201], v145 offset:21504
	ds_read_b128 v[202:205], v145 offset:22528
	ds_read_b128 v[206:209], v145 offset:23552
	global_load_lds_dwordx4 v[158:159], off
	s_add_i32 m0, s24, 0x2000
	s_add_u32 s24, s60, 0x80000
	v_lshl_add_u64 v[210:211], s[60:61], 0, v[132:133]
	s_addc_u32 s25, s61, 0
	s_add_i32 s26, s27, s35
	global_load_lds_dwordx4 v[210:211], off
	v_lshl_add_u64 v[212:213], s[24:25], 0, v[160:161]
	s_mov_b32 m0, s26
	v_lshl_add_u64 v[214:215], s[62:63], 0, v[130:131]
	global_load_lds_dwordx4 v[212:213], off
	v_lshl_add_u64 v[212:213], s[24:25], 0, v[132:133]
	s_add_i32 m0, s26, 0x2000
	s_nop 0
	global_load_lds_dwordx4 v[212:213], off
	v_lshl_add_u64 v[212:213], s[62:63], 0, v[128:129]
	s_mov_b32 m0, s57
	s_nop 0
	global_load_lds_dwordx4 v[212:213], off
	s_mov_b32 m0, s64
	s_nop 0
	global_load_lds_dwordx4 v[214:215], off
	s_waitcnt vmcnt(8)
	s_waitcnt lgkmcnt(0)
	s_barrier
; #define PG8_STAGE(bufoff, gbase, voff) do { _Pragma("unroll") for (int _i = 0; _i < 2; ++_i) \
;         __builtin_amdgcn_global_load_lds((const unsigned*)((const char*)(gbase) + (voff)[_i]), (PG8_LAS unsigned*)(lds + (bufoff) + ldsw + _i * 8192), 16, 0, 0); } while (0)
; #define PG8_LDA(dst, b, h) do { _Pragma("unroll") for (int m = 0; m < 4; ++m) _Pragma("unroll") for (int k = 0; k < 2; ++k) dst[m][k] = *(const PG8_LAS bf16x8*)(lds + PG8_SA(b, h) + aoff + m * 2048 + k * 1024); } while (0)
; #define PG8_LDB(dst, b, h) do { _Pragma("unroll") for (int n = 0; n < 2; ++n) _Pragma("unroll") for (int k = 0; k < 2; ++k) dst[n][k] = *(const PG8_LAS bf16x8*)(lds + PG8_SB(b, h) + boff + n * 2048 + k * 1024); } while (0)
; #define PG8_MMA(ai, bj, At, Bt) do { __builtin_amdgcn_s_setprio(1); _Pragma("unroll") for (int m = 0; m < 4; ++m) _Pragma("unroll") for (int n = 0; n < 2; ++n) _Pragma("unroll") for (int k = 0; k < 2; ++k) \
;         acc[ai][bj][m][n] = __builtin_amdgcn_mfma_f32_16x16x32_bf16(Bt[n][k], At[m][k], acc[ai][bj][m][n], 0, 0, 0); __builtin_amdgcn_s_setprio(0); } while (0)
; #define PG8_WAIT_V(n) asm volatile("s_waitcnt vmcnt(" #n ")" ::: "memory")
; #define PG8_WAIT_L(n) asm volatile("s_waitcnt lgkmcnt(" #n ")" ::: "memory")
; #define PG8_BAR __builtin_amdgcn_s_barrier()
; #define PG8_SCHED __builtin_amdgcn_sched_barrier(0)
; template <class Epi, class Sched, bool ALIGN_EPI = false, bool SP2 = false>
; __device__ __forceinline__ void gemm_phase(PG8_LAS unsigned char* lds, const Gemm g, const Sched& S, const Epi& E, const int wid_in) {
;     ...
;             PG8_WAIT_V(8); PG8_WAIT_L(0); PG8_BAR; PG8_MMA(1, 0, At, B0); PG8_MMA(1, 1, At, B1); PG8_BAR; PG8_SCHED;
;             PG8_LDB(B0, 1, 0); PG8_LDB(B1, 1, 1); PG8_SCHED; PG8_LDA(At, 1, 0); PG8_STAGE(PG8_SA(0, 1), a2 + hstep, voffA);
;             PG8_WAIT_V(8); PG8_WAIT_L(0); PG8_BAR; PG8_MMA(0, 0, At, B0); PG8_MMA(0, 1, At, B1); PG8_BAR; PG8_SCHED;
	s_setprio 1
	s_waitcnt lgkmcnt(0)
	v_mfma_f32_16x16x32_bf16 v[60:63], v[138:141], v[178:181], v[60:63]
	v_mfma_f32_16x16x32_bf16 v[56:59], v[150:153], v[178:181], v[56:59]
	v_mfma_f32_16x16x32_bf16 v[52:55], v[138:141], v[186:189], v[52:55]
	v_mfma_f32_16x16x32_bf16 v[44:47], v[150:153], v[186:189], v[44:47]
	v_mfma_f32_16x16x32_bf16 v[36:39], v[138:141], v[194:197], v[36:39]
	v_mfma_f32_16x16x32_bf16 v[28:31], v[150:153], v[194:197], v[28:31]
	v_mfma_f32_16x16x32_bf16 v[20:23], v[138:141], v[202:205], v[20:23]
	v_mfma_f32_16x16x32_bf16 v[12:15], v[150:153], v[202:205], v[12:15]
	v_mfma_f32_16x16x32_bf16 v[60:63], v[146:149], v[182:185], v[60:63]
	v_mfma_f32_16x16x32_bf16 v[56:59], v[154:157], v[182:185], v[56:59]
	v_mfma_f32_16x16x32_bf16 v[52:55], v[146:149], v[190:193], v[52:55]
	v_mfma_f32_16x16x32_bf16 v[44:47], v[154:157], v[190:193], v[44:47]
	v_mfma_f32_16x16x32_bf16 v[36:39], v[146:149], v[198:201], v[36:39]
	v_mfma_f32_16x16x32_bf16 v[28:31], v[154:157], v[198:201], v[28:31]
	v_mfma_f32_16x16x32_bf16 v[20:23], v[146:149], v[206:209], v[20:23]
	v_mfma_f32_16x16x32_bf16 v[12:15], v[154:157], v[206:209], v[12:15]
	s_setprio 0
	s_setprio 1
	v_mfma_f32_16x16x32_bf16 v[48:51], v[162:165], v[178:181], v[48:51]
	v_mfma_f32_16x16x32_bf16 v[40:43], v[170:173], v[178:181], v[40:43]
	v_mfma_f32_16x16x32_bf16 v[32:35], v[162:165], v[186:189], v[32:35]
	v_mfma_f32_16x16x32_bf16 v[24:27], v[170:173], v[186:189], v[24:27]
	v_mfma_f32_16x16x32_bf16 v[16:19], v[162:165], v[194:197], v[16:19]
	v_mfma_f32_16x16x32_bf16 v[8:11], v[170:173], v[194:197], v[8:11]
	v_mfma_f32_16x16x32_bf16 v[4:7], v[162:165], v[202:205], v[4:7]
	v_mfma_f32_16x16x32_bf16 v[0:3], v[170:173], v[202:205], v[0:3]
	v_mfma_f32_16x16x32_bf16 v[48:51], v[166:169], v[182:185], v[48:51]
	v_mfma_f32_16x16x32_bf16 v[40:43], v[174:177], v[182:185], v[40:43]
	v_mfma_f32_16x16x32_bf16 v[32:35], v[166:169], v[190:193], v[32:35]
	v_mfma_f32_16x16x32_bf16 v[24:27], v[174:177], v[190:193], v[24:27]
	v_mfma_f32_16x16x32_bf16 v[16:19], v[166:169], v[198:201], v[16:19]
	v_mfma_f32_16x16x32_bf16 v[8:11], v[174:177], v[198:201], v[8:11]
	v_mfma_f32_16x16x32_bf16 v[4:7], v[166:169], v[206:209], v[4:7]
	v_mfma_f32_16x16x32_bf16 v[0:3], v[174:177], v[206:209], v[0:3]
	s_setprio 0
	s_barrier
	s_add_i32 s26, 0, 0x18000
	s_add_i32 s27, 0, 0x1c000
	v_add_u32_e32 v154, s26, v143
	v_add_u32_e32 v174, s27, v143
	ds_read_b128 v[138:141], v154
	ds_read_b128 v[146:149], v154 offset:1024
	ds_read_b128 v[150:153], v154 offset:2048
	ds_read_b128 v[154:157], v154 offset:3072
	ds_read_b128 v[162:165], v174
	ds_read_b128 v[166:169], v174 offset:1024
	ds_read_b128 v[170:173], v174 offset:2048
	ds_read_b128 v[174:177], v174 offset:3072
	s_add_u32 s24, s62, 0x80000
	s_addc_u32 s25, s63, 0
	s_mov_b32 m0, s65
	v_lshl_add_u64 v[216:217], s[24:25], 0, v[128:129]
	ds_read_b128 v[178:181], v145 offset:32768
	ds_read_b128 v[182:185], v145 offset:33792
	ds_read_b128 v[186:189], v145 offset:34816
	ds_read_b128 v[190:193], v145 offset:35840
	ds_read_b128 v[194:197], v145 offset:36864
	ds_read_b128 v[198:201], v145 offset:37888
	ds_read_b128 v[202:205], v145 offset:38912
	ds_read_b128 v[206:209], v145 offset:39936
	global_load_lds_dwordx4 v[216:217], off
	v_lshl_add_u64 v[216:217], s[24:25], 0, v[130:131]
	s_mov_b32 m0, s66
	s_nop 0
	global_load_lds_dwordx4 v[216:217], off
	s_waitcnt vmcnt(8)
	s_waitcnt lgkmcnt(0)
	s_barrier
	s_setprio 1
	s_waitcnt lgkmcnt(0)
	v_mfma_f32_16x16x32_bf16 v[124:127], v[138:141], v[178:181], v[124:127]
	v_mfma_f32_16x16x32_bf16 v[120:123], v[150:153], v[178:181], v[120:123]
	v_mfma_f32_16x16x32_bf16 v[116:119], v[138:141], v[186:189], v[116:119]
	v_mfma_f32_16x16x32_bf16 v[108:111], v[150:153], v[186:189], v[108:111]
	v_mfma_f32_16x16x32_bf16 v[100:103], v[138:141], v[194:197], v[100:103]
	v_mfma_f32_16x16x32_bf16 v[92:95], v[150:153], v[194:197], v[92:95]
	v_mfma_f32_16x16x32_bf16 v[84:87], v[138:141], v[202:205], v[84:87]
	v_mfma_f32_16x16x32_bf16 v[76:79], v[150:153], v[202:205], v[76:79]
	v_mfma_f32_16x16x32_bf16 v[124:127], v[146:149], v[182:185], v[124:127]
	v_mfma_f32_16x16x32_bf16 v[120:123], v[154:157], v[182:185], v[120:123]
	v_mfma_f32_16x16x32_bf16 v[116:119], v[146:149], v[190:193], v[116:119]
	v_mfma_f32_16x16x32_bf16 v[108:111], v[154:157], v[190:193], v[108:111]
	v_mfma_f32_16x16x32_bf16 v[100:103], v[146:149], v[198:201], v[100:103]
	v_mfma_f32_16x16x32_bf16 v[92:95], v[154:157], v[198:201], v[92:95]
	v_mfma_f32_16x16x32_bf16 v[84:87], v[146:149], v[206:209], v[84:87]
	v_mfma_f32_16x16x32_bf16 v[76:79], v[154:157], v[206:209], v[76:79]
	s_setprio 0
	s_setprio 1
	v_mfma_f32_16x16x32_bf16 v[112:115], v[162:165], v[178:181], v[112:115]
	v_mfma_f32_16x16x32_bf16 v[104:107], v[170:173], v[178:181], v[104:107]
	v_mfma_f32_16x16x32_bf16 v[96:99], v[162:165], v[186:189], v[96:99]
	v_mfma_f32_16x16x32_bf16 v[88:91], v[170:173], v[186:189], v[88:91]
	v_mfma_f32_16x16x32_bf16 v[80:83], v[162:165], v[194:197], v[80:83]
	v_mfma_f32_16x16x32_bf16 v[72:75], v[170:173], v[194:197], v[72:75]
	v_mfma_f32_16x16x32_bf16 v[68:71], v[162:165], v[202:205], v[68:71]
	v_mfma_f32_16x16x32_bf16 v[64:67], v[170:173], v[202:205], v[64:67]
	v_mfma_f32_16x16x32_bf16 v[112:115], v[166:169], v[182:185], v[112:115]
	v_mfma_f32_16x16x32_bf16 v[104:107], v[174:177], v[182:185], v[104:107]
	v_mfma_f32_16x16x32_bf16 v[96:99], v[166:169], v[190:193], v[96:99]
	v_mfma_f32_16x16x32_bf16 v[88:91], v[174:177], v[190:193], v[88:91]
	v_mfma_f32_16x16x32_bf16 v[80:83], v[166:169], v[198:201], v[80:83]
	v_mfma_f32_16x16x32_bf16 v[72:75], v[174:177], v[198:201], v[72:75]
	v_mfma_f32_16x16x32_bf16 v[68:71], v[166:169], v[206:209], v[68:71]
	v_mfma_f32_16x16x32_bf16 v[64:67], v[174:177], v[206:209], v[64:67]
	s_setprio 0
	s_barrier
; #define PG8_STAGE(bufoff, gbase, voff) do { _Pragma("unroll") for (int _i = 0; _i < 2; ++_i) \
;         __builtin_amdgcn_global_load_lds((const unsigned*)((const char*)(gbase) + (voff)[_i]), (PG8_LAS unsigned*)(lds + (bufoff) + ldsw + _i * 8192), 16, 0, 0); } while (0)
; #define PG8_LDA(dst, b, h) do { _Pragma("unroll") for (int m = 0; m < 4; ++m) _Pragma("unroll") for (int k = 0; k < 2; ++k) dst[m][k] = *(const PG8_LAS bf16x8*)(lds + PG8_SA(b, h) + aoff + m * 2048 + k * 1024); } while (0)
; #define PG8_MMA(ai, bj, At, Bt) do { __builtin_amdgcn_s_setprio(1); _Pragma("unroll") for (int m = 0; m < 4; ++m) _Pragma("unroll") for (int n = 0; n < 2; ++n) _Pragma("unroll") for (int k = 0; k < 2; ++k) \
;         acc[ai][bj][m][n] = __builtin_amdgcn_mfma_f32_16x16x32_bf16(Bt[n][k], At[m][k], acc[ai][bj][m][n], 0, 0, 0); __builtin_amdgcn_s_setprio(0); } while (0)
; #define PG8_WAIT_V(n) asm volatile("s_waitcnt vmcnt(" #n ")" ::: "memory")
; #define PG8_WAIT_L(n) asm volatile("s_waitcnt lgkmcnt(" #n ")" ::: "memory")
; #define PG8_BAR __builtin_amdgcn_s_barrier()
; #define PG8_SCHED __builtin_amdgcn_sched_barrier(0)
; template <class Epi, class Sched, bool ALIGN_EPI = false, bool SP2 = false>
; __device__ __forceinline__ void gemm_phase(PG8_LAS unsigned char* lds, const Gemm g, const Sched& S, const Epi& E, const int wid_in) {
;     ...
;         for (int t = 0; t < nt; t += 2) {
;             const bool last = (t == nt - 2);
;     ...
;             PG8_WAIT_V(8); PG8_WAIT_L(0); PG8_BAR; PG8_MMA(0, 0, At, B0); PG8_MMA(0, 1, At, B1); PG8_BAR; PG8_SCHED;
;             PG8_LDA(At, 1, 1); PG8_STAGE(PG8_SB(1, 0), b3, voffB); PG8_STAGE(PG8_SB(1, 1), b3 + hstep, voffB); PG8_STAGE(PG8_SA(1, 0), a3, voffA);
;             PG8_WAIT_V(8); PG8_WAIT_L(0); PG8_BAR; PG8_MMA(1, 0, At, B0); PG8_MMA(1, 1, At, B1); PG8_BAR; PG8_SCHED;
	s_add_i32 s24, s26, s35
	v_lshl_add_u64 v[158:159], v[158:159], 0, s[8:9]
	s_mov_b32 m0, s24
	ds_read_b128 v[178:181], v145 offset:49152
	ds_read_b128 v[182:185], v145 offset:50176
	ds_read_b128 v[186:189], v145 offset:51200
	ds_read_b128 v[190:193], v145 offset:52224
	ds_read_b128 v[194:197], v145 offset:53248
	ds_read_b128 v[198:201], v145 offset:54272
	ds_read_b128 v[202:205], v145 offset:55296
	ds_read_b128 v[206:209], v145 offset:56320
	global_load_lds_dwordx4 v[158:159], off
	s_add_i32 m0, s24, 0x2000
	s_add_u32 s24, s60, 0x80080
	v_lshl_add_u64 v[158:159], v[210:211], 0, s[8:9]
	s_addc_u32 s25, s61, 0
	s_add_i32 s26, s27, s35
	global_load_lds_dwordx4 v[158:159], off
	v_lshl_add_u64 v[158:159], s[24:25], 0, v[160:161]
	s_mov_b32 m0, s26
	s_nop 0
	global_load_lds_dwordx4 v[158:159], off
	v_lshl_add_u64 v[158:159], s[24:25], 0, v[132:133]
	s_add_i32 m0, s26, 0x2000
	s_nop 0
	global_load_lds_dwordx4 v[158:159], off
	v_lshl_add_u64 v[158:159], v[212:213], 0, s[8:9]
	s_mov_b32 m0, s67
	s_nop 0
	global_load_lds_dwordx4 v[158:159], off
	v_lshl_add_u64 v[158:159], v[214:215], 0, s[8:9]
	s_mov_b32 m0, s68
	s_nop 0
	global_load_lds_dwordx4 v[158:159], off
	s_waitcnt vmcnt(8)
	s_waitcnt lgkmcnt(0)
	s_barrier
	s_setprio 1
	s_waitcnt lgkmcnt(0)
	v_mfma_f32_16x16x32_bf16 v[60:63], v[138:141], v[178:181], v[60:63]
	v_mfma_f32_16x16x32_bf16 v[56:59], v[150:153], v[178:181], v[56:59]
	v_mfma_f32_16x16x32_bf16 v[52:55], v[138:141], v[186:189], v[52:55]
	v_mfma_f32_16x16x32_bf16 v[44:47], v[150:153], v[186:189], v[44:47]
	v_mfma_f32_16x16x32_bf16 v[36:39], v[138:141], v[194:197], v[36:39]
	v_mfma_f32_16x16x32_bf16 v[28:31], v[150:153], v[194:197], v[28:31]
	v_mfma_f32_16x16x32_bf16 v[20:23], v[138:141], v[202:205], v[20:23]
	v_mfma_f32_16x16x32_bf16 v[12:15], v[150:153], v[202:205], v[12:15]
	v_mfma_f32_16x16x32_bf16 v[60:63], v[146:149], v[182:185], v[60:63]
	v_mfma_f32_16x16x32_bf16 v[56:59], v[154:157], v[182:185], v[56:59]
	v_mfma_f32_16x16x32_bf16 v[52:55], v[146:149], v[190:193], v[52:55]
	v_mfma_f32_16x16x32_bf16 v[44:47], v[154:157], v[190:193], v[44:47]
	v_mfma_f32_16x16x32_bf16 v[36:39], v[146:149], v[198:201], v[36:39]
	v_mfma_f32_16x16x32_bf16 v[28:31], v[154:157], v[198:201], v[28:31]
	v_mfma_f32_16x16x32_bf16 v[20:23], v[146:149], v[206:209], v[20:23]
	v_mfma_f32_16x16x32_bf16 v[12:15], v[154:157], v[206:209], v[12:15]
	s_setprio 0
	s_setprio 1
	v_mfma_f32_16x16x32_bf16 v[48:51], v[162:165], v[178:181], v[48:51]
	v_mfma_f32_16x16x32_bf16 v[40:43], v[170:173], v[178:181], v[40:43]
	v_mfma_f32_16x16x32_bf16 v[32:35], v[162:165], v[186:189], v[32:35]
	v_mfma_f32_16x16x32_bf16 v[24:27], v[170:173], v[186:189], v[24:27]
	v_mfma_f32_16x16x32_bf16 v[16:19], v[162:165], v[194:197], v[16:19]
	v_mfma_f32_16x16x32_bf16 v[8:11], v[170:173], v[194:197], v[8:11]
	v_mfma_f32_16x16x32_bf16 v[4:7], v[162:165], v[202:205], v[4:7]
	v_mfma_f32_16x16x32_bf16 v[0:3], v[170:173], v[202:205], v[0:3]
	v_mfma_f32_16x16x32_bf16 v[48:51], v[166:169], v[182:185], v[48:51]
	v_mfma_f32_16x16x32_bf16 v[40:43], v[174:177], v[182:185], v[40:43]
	v_mfma_f32_16x16x32_bf16 v[32:35], v[166:169], v[190:193], v[32:35]
	v_mfma_f32_16x16x32_bf16 v[24:27], v[174:177], v[190:193], v[24:27]
	v_mfma_f32_16x16x32_bf16 v[16:19], v[166:169], v[198:201], v[16:19]
	v_mfma_f32_16x16x32_bf16 v[8:11], v[174:177], v[198:201], v[8:11]
	v_mfma_f32_16x16x32_bf16 v[4:7], v[166:169], v[206:209], v[4:7]
	v_mfma_f32_16x16x32_bf16 v[0:3], v[174:177], v[206:209], v[0:3]
	s_setprio 0
	s_add_i32 s73, s73, 2
	s_add_u32 s58, s58, 0x100
	s_addc_u32 s59, s59, 0
	s_add_u32 s71, s71, 0x100
	s_addc_u32 s72, s72, 0
	s_cmp_gt_u32 s73, 29
	s_barrier
	s_cbranch_scc0 .LBB0_674
	s_and_b64 vcc, exec, s[46:47]
	s_cbranch_vccz .LBB0_677
	s_barrier

; #define PG8_STAGE(bufoff, gbase, voff) do { _Pragma("unroll") for (int _i = 0; _i < 2; ++_i) \
;         __builtin_amdgcn_global_load_lds((const unsigned*)((const char*)(gbase) + (voff)[_i]), (PG8_LAS unsigned*)(lds + (bufoff) + ldsw + _i * 8192), 16, 0, 0); } while (0)
; #define PG8_LDA(dst, b, h) do { _Pragma("unroll") for (int m = 0; m < 4; ++m) _Pragma("unroll") for (int k = 0; k < 2; ++k) dst[m][k] = *(const PG8_LAS bf16x8*)(lds + PG8_SA(b, h) + aoff + m * 2048 + k * 1024); } while (0)
; #define PG8_LDB(dst, b, h) do { _Pragma("unroll") for (int n = 0; n < 2; ++n) _Pragma("unroll") for (int k = 0; k < 2; ++k) dst[n][k] = *(const PG8_LAS bf16x8*)(lds + PG8_SB(b, h) + boff + n * 2048 + k * 1024); } while (0)
; #define PG8_MMA(ai, bj, At, Bt) do { __builtin_amdgcn_s_setprio(1); _Pragma("unroll") for (int m = 0; m < 4; ++m) _Pragma("unroll") for (int n = 0; n < 2; ++n) _Pragma("unroll") for (int k = 0; k < 2; ++k) \
;         acc[ai][bj][m][n] = __builtin_amdgcn_mfma_f32_16x16x32_bf16(Bt[n][k], At[m][k], acc[ai][bj][m][n], 0, 0, 0); __builtin_amdgcn_s_setprio(0); } while (0)
; #define PG8_WAIT_V(n) asm volatile("s_waitcnt vmcnt(" #n ")" ::: "memory")
; #define PG8_WAIT_L(n) asm volatile("s_waitcnt lgkmcnt(" #n ")" ::: "memory")
; #define PG8_BAR __builtin_amdgcn_s_barrier()
; template <class Epi, class Sched, bool ALIGN_EPI = false, bool SP2 = false>
; __device__ __forceinline__ void gemm_phase(PG8_LAS unsigned char* lds, const Gemm g, const Sched& S, const Epi& E, const int wid_in) {
;     ...
;         for (int t = 0; t < nt; t += 2) {
;             const bool last = (t == nt - 2);
;             const char* a1 = cA + (size_t)(t + 1) * kstep;
;             const char* a2 = last ? nA : cA + (size_t)(t + 2) * kstep; const char* b2 = last ? nB : cB + (size_t)(t + 2) * kstep;
;             const char* a3 = a2 + kstep; const char* b3 = b2 + kstep;
;             if (last && has_next) S.a_ready(nxt);
;             if constexpr (SP2) {
;             PG8_LDB(B0, 0, 0); PG8_LDB(B1, 0, 1); PG8_SCHED; PG8_LDA(At, 0, 0); PG8_STAGE(PG8_SA(1, 1), a1 + hstep, voffA);
;             PG8_WAIT_V(8); PG8_WAIT_L(0); PG8_BAR; PG8_MMA(0, 0, At, B0); PG8_MMA(0, 1, At, B1); PG8_BAR; PG8_SCHED;
;             PG8_LDA(At, 0, 1); PG8_STAGE(PG8_SB(0, 0), b2, voffB); PG8_STAGE(PG8_SB(0, 1), b2 + hstep, voffB); PG8_STAGE(PG8_SA(0, 0), a2, voffA);
.LBB0_814:
	s_add_u32 s24, s62, 0xfff80080
	s_addc_u32 s25, s63, -1
	s_add_i32 s26, 0, 0x10000
	s_cmp_eq_u32 s39, 28
	s_cselect_b32 s67, s6, s25
	s_cselect_b32 s66, s7, s24
	s_cselect_b32 s65, s14, s35
	s_cselect_b32 s64, s15, s34
	s_add_i32 s27, 0, 0x14000
	v_add_u32_e32 v140, s26, v250
	v_add_u32_e32 v156, s27, v250
	ds_read_b128 v[128:131], v140
	ds_read_b128 v[132:135], v140 offset:1024
	ds_read_b128 v[136:139], v140 offset:2048
	ds_read_b128 v[140:143], v140 offset:3072
	ds_read_b128 v[144:147], v156
	ds_read_b128 v[148:151], v156 offset:1024
	ds_read_b128 v[152:155], v156 offset:2048
	ds_read_b128 v[156:159], v156 offset:3072
	v_lshl_add_u64 v[164:165], s[62:63], 0, v[174:175]
	s_add_i32 m0, s75, 0xc000
	ds_read_b128 v[178:181], v162
	ds_read_b128 v[182:185], v162 offset:1024
	ds_read_b128 v[186:189], v162 offset:2048
	ds_read_b128 v[190:193], v162 offset:3072
	ds_read_b128 v[194:197], v162 offset:4096
	ds_read_b128 v[198:201], v162 offset:5120
	ds_read_b128 v[202:205], v162 offset:6144
	ds_read_b128 v[206:209], v162 offset:7168
	global_load_lds_dwordx4 v[164:165], off
	v_lshl_add_u64 v[164:165], s[62:63], 0, v[176:177]
	s_add_i32 m0, s75, 0xe000
	s_nop 0
	global_load_lds_dwordx4 v[164:165], off
	s_waitcnt vmcnt(8)
	s_waitcnt lgkmcnt(0)
	s_barrier
	s_setprio 1
	s_waitcnt lgkmcnt(0)
	v_mfma_f32_16x16x32_bf16 v[124:127], v[128:131], v[178:181], v[124:127]
	v_mfma_f32_16x16x32_bf16 v[120:123], v[136:139], v[178:181], v[120:123]
	v_mfma_f32_16x16x32_bf16 v[108:111], v[128:131], v[186:189], v[108:111]
	v_mfma_f32_16x16x32_bf16 v[104:107], v[136:139], v[186:189], v[104:107]
	v_mfma_f32_16x16x32_bf16 v[92:95], v[128:131], v[194:197], v[92:95]
	v_mfma_f32_16x16x32_bf16 v[88:91], v[136:139], v[194:197], v[88:91]
	v_mfma_f32_16x16x32_bf16 v[76:79], v[128:131], v[202:205], v[76:79]
	v_mfma_f32_16x16x32_bf16 v[72:75], v[136:139], v[202:205], v[72:75]
	v_mfma_f32_16x16x32_bf16 v[124:127], v[132:135], v[182:185], v[124:127]
	v_mfma_f32_16x16x32_bf16 v[120:123], v[140:143], v[182:185], v[120:123]
	v_mfma_f32_16x16x32_bf16 v[108:111], v[132:135], v[190:193], v[108:111]
	v_mfma_f32_16x16x32_bf16 v[104:107], v[140:143], v[190:193], v[104:107]
	v_mfma_f32_16x16x32_bf16 v[92:95], v[132:135], v[198:201], v[92:95]
	v_mfma_f32_16x16x32_bf16 v[88:91], v[140:143], v[198:201], v[88:91]
	v_mfma_f32_16x16x32_bf16 v[76:79], v[132:135], v[206:209], v[76:79]
	v_mfma_f32_16x16x32_bf16 v[72:75], v[140:143], v[206:209], v[72:75]
	s_setprio 0
	s_setprio 1
	v_mfma_f32_16x16x32_bf16 v[116:119], v[144:147], v[178:181], v[116:119]
	v_mfma_f32_16x16x32_bf16 v[112:115], v[152:155], v[178:181], v[112:115]
	v_mfma_f32_16x16x32_bf16 v[100:103], v[144:147], v[186:189], v[100:103]
	v_mfma_f32_16x16x32_bf16 v[96:99], v[152:155], v[186:189], v[96:99]
	v_mfma_f32_16x16x32_bf16 v[84:87], v[144:147], v[194:197], v[84:87]
	v_mfma_f32_16x16x32_bf16 v[80:83], v[152:155], v[194:197], v[80:83]
	v_mfma_f32_16x16x32_bf16 v[68:71], v[144:147], v[202:205], v[68:71]
	v_mfma_f32_16x16x32_bf16 v[64:67], v[152:155], v[202:205], v[64:67]
	v_mfma_f32_16x16x32_bf16 v[116:119], v[148:151], v[182:185], v[116:119]
	v_mfma_f32_16x16x32_bf16 v[112:115], v[156:159], v[182:185], v[112:115]
	v_mfma_f32_16x16x32_bf16 v[100:103], v[148:151], v[190:193], v[100:103]
	v_mfma_f32_16x16x32_bf16 v[96:99], v[156:159], v[190:193], v[96:99]
	v_mfma_f32_16x16x32_bf16 v[84:87], v[148:151], v[198:201], v[84:87]
	v_mfma_f32_16x16x32_bf16 v[80:83], v[156:159], v[198:201], v[80:83]
	v_mfma_f32_16x16x32_bf16 v[68:71], v[148:151], v[206:209], v[68:71]
	v_mfma_f32_16x16x32_bf16 v[64:67], v[156:159], v[206:209], v[64:67]
	s_setprio 0
	s_barrier
	s_add_i32 s24, s26, s74
	v_lshl_add_u64 v[164:165], s[64:65], 0, v[168:169]
	s_mov_b32 m0, s24
	ds_read_b128 v[178:181], v162 offset:16384
	ds_read_b128 v[182:185], v162 offset:17408
	ds_read_b128 v[186:189], v162 offset:18432
	ds_read_b128 v[190:193], v162 offset:19456
	ds_read_b128 v[194:197], v162 offset:20480
	ds_read_b128 v[198:201], v162 offset:21504
	ds_read_b128 v[202:205], v162 offset:22528
	ds_read_b128 v[206:209], v162 offset:23552
	global_load_lds_dwordx4 v[164:165], off
	s_add_i32 m0, s24, 0x2000
	s_add_u32 s24, s64, 0x80000
	v_lshl_add_u64 v[210:211], s[64:65], 0, v[172:173]
	s_addc_u32 s25, s65, 0
	s_add_i32 s26, s27, s74
	global_load_lds_dwordx4 v[210:211], off
	v_lshl_add_u64 v[212:213], s[24:25], 0, v[168:169]
	s_mov_b32 m0, s26
	v_lshl_add_u64 v[214:215], s[66:67], 0, v[170:171]
	global_load_lds_dwordx4 v[212:213], off
	v_lshl_add_u64 v[212:213], s[24:25], 0, v[172:173]
	s_add_i32 m0, s26, 0x2000
	s_nop 0
	global_load_lds_dwordx4 v[212:213], off
	v_lshl_add_u64 v[212:213], s[66:67], 0, v[166:167]
	s_mov_b32 m0, s75
	s_nop 0
	global_load_lds_dwordx4 v[212:213], off
	s_mov_b32 m0, s76
	s_nop 0
	global_load_lds_dwordx4 v[214:215], off
	s_waitcnt vmcnt(8)
	s_waitcnt lgkmcnt(0)
	s_barrier
; #define PG8_STAGE(bufoff, gbase, voff) do { _Pragma("unroll") for (int _i = 0; _i < 2; ++_i) \
;         __builtin_amdgcn_global_load_lds((const unsigned*)((const char*)(gbase) + (voff)[_i]), (PG8_LAS unsigned*)(lds + (bufoff) + ldsw + _i * 8192), 16, 0, 0); } while (0)
; #define PG8_LDA(dst, b, h) do { _Pragma("unroll") for (int m = 0; m < 4; ++m) _Pragma("unroll") for (int k = 0; k < 2; ++k) dst[m][k] = *(const PG8_LAS bf16x8*)(lds + PG8_SA(b, h) + aoff + m * 2048 + k * 1024); } while (0)
; #define PG8_LDB(dst, b, h) do { _Pragma("unroll") for (int n = 0; n < 2; ++n) _Pragma("unroll") for (int k = 0; k < 2; ++k) dst[n][k] = *(const PG8_LAS bf16x8*)(lds + PG8_SB(b, h) + boff + n * 2048 + k * 1024); } while (0)
; #define PG8_MMA(ai, bj, At, Bt) do { __builtin_amdgcn_s_setprio(1); _Pragma("unroll") for (int m = 0; m < 4; ++m) _Pragma("unroll") for (int n = 0; n < 2; ++n) _Pragma("unroll") for (int k = 0; k < 2; ++k) \
;         acc[ai][bj][m][n] = __builtin_amdgcn_mfma_f32_16x16x32_bf16(Bt[n][k], At[m][k], acc[ai][bj][m][n], 0, 0, 0); __builtin_amdgcn_s_setprio(0); } while (0)
; #define PG8_WAIT_V(n) asm volatile("s_waitcnt vmcnt(" #n ")" ::: "memory")
; #define PG8_WAIT_L(n) asm volatile("s_waitcnt lgkmcnt(" #n ")" ::: "memory")
; #define PG8_BAR __builtin_amdgcn_s_barrier()
; #define PG8_SCHED __builtin_amdgcn_sched_barrier(0)
; template <class Epi, class Sched, bool ALIGN_EPI = false, bool SP2 = false>
; __device__ __forceinline__ void gemm_phase(PG8_LAS unsigned char* lds, const Gemm g, const Sched& S, const Epi& E, const int wid_in) {
;     ...
;             PG8_WAIT_V(8); PG8_WAIT_L(0); PG8_BAR; PG8_MMA(1, 0, At, B0); PG8_MMA(1, 1, At, B1); PG8_BAR; PG8_SCHED;
;             PG8_LDB(B0, 1, 0); PG8_LDB(B1, 1, 1); PG8_SCHED; PG8_LDA(At, 1, 0); PG8_STAGE(PG8_SA(0, 1), a2 + hstep, voffA);
;             PG8_WAIT_V(8); PG8_WAIT_L(0); PG8_BAR; PG8_MMA(0, 0, At, B0); PG8_MMA(0, 1, At, B1); PG8_BAR; PG8_SCHED;
	s_setprio 1
	s_waitcnt lgkmcnt(0)
	v_mfma_f32_16x16x32_bf16 v[60:63], v[128:131], v[178:181], v[60:63]
	v_mfma_f32_16x16x32_bf16 v[56:59], v[136:139], v[178:181], v[56:59]
	v_mfma_f32_16x16x32_bf16 v[44:47], v[128:131], v[186:189], v[44:47]
	v_mfma_f32_16x16x32_bf16 v[40:43], v[136:139], v[186:189], v[40:43]
	v_mfma_f32_16x16x32_bf16 v[28:31], v[128:131], v[194:197], v[28:31]
	v_mfma_f32_16x16x32_bf16 v[24:27], v[136:139], v[194:197], v[24:27]
	v_mfma_f32_16x16x32_bf16 v[12:15], v[128:131], v[202:205], v[12:15]
	v_mfma_f32_16x16x32_bf16 v[8:11], v[136:139], v[202:205], v[8:11]
	v_mfma_f32_16x16x32_bf16 v[60:63], v[132:135], v[182:185], v[60:63]
	v_mfma_f32_16x16x32_bf16 v[56:59], v[140:143], v[182:185], v[56:59]
	v_mfma_f32_16x16x32_bf16 v[44:47], v[132:135], v[190:193], v[44:47]
	v_mfma_f32_16x16x32_bf16 v[40:43], v[140:143], v[190:193], v[40:43]
	v_mfma_f32_16x16x32_bf16 v[28:31], v[132:135], v[198:201], v[28:31]
	v_mfma_f32_16x16x32_bf16 v[24:27], v[140:143], v[198:201], v[24:27]
	v_mfma_f32_16x16x32_bf16 v[12:15], v[132:135], v[206:209], v[12:15]
	v_mfma_f32_16x16x32_bf16 v[8:11], v[140:143], v[206:209], v[8:11]
	s_setprio 0
	s_setprio 1
	v_mfma_f32_16x16x32_bf16 v[52:55], v[144:147], v[178:181], v[52:55]
	v_mfma_f32_16x16x32_bf16 v[48:51], v[152:155], v[178:181], v[48:51]
	v_mfma_f32_16x16x32_bf16 v[36:39], v[144:147], v[186:189], v[36:39]
	v_mfma_f32_16x16x32_bf16 v[32:35], v[152:155], v[186:189], v[32:35]
	v_mfma_f32_16x16x32_bf16 v[20:23], v[144:147], v[194:197], v[20:23]
	v_mfma_f32_16x16x32_bf16 v[16:19], v[152:155], v[194:197], v[16:19]
	v_mfma_f32_16x16x32_bf16 v[4:7], v[144:147], v[202:205], v[4:7]
	v_mfma_f32_16x16x32_bf16 v[0:3], v[152:155], v[202:205], v[0:3]
	v_mfma_f32_16x16x32_bf16 v[52:55], v[148:151], v[182:185], v[52:55]
	v_mfma_f32_16x16x32_bf16 v[48:51], v[156:159], v[182:185], v[48:51]
	v_mfma_f32_16x16x32_bf16 v[36:39], v[148:151], v[190:193], v[36:39]
	v_mfma_f32_16x16x32_bf16 v[32:35], v[156:159], v[190:193], v[32:35]
	v_mfma_f32_16x16x32_bf16 v[20:23], v[148:151], v[198:201], v[20:23]
	v_mfma_f32_16x16x32_bf16 v[16:19], v[156:159], v[198:201], v[16:19]
	v_mfma_f32_16x16x32_bf16 v[4:7], v[148:151], v[206:209], v[4:7]
	v_mfma_f32_16x16x32_bf16 v[0:3], v[156:159], v[206:209], v[0:3]
	s_setprio 0
	s_barrier
	s_add_i32 s26, 0, 0x18000
	s_add_i32 s27, 0, 0x1c000
	v_add_u32_e32 v140, s26, v250
	v_add_u32_e32 v156, s27, v250
	ds_read_b128 v[128:131], v140
	ds_read_b128 v[132:135], v140 offset:1024
	ds_read_b128 v[136:139], v140 offset:2048
	ds_read_b128 v[140:143], v140 offset:3072
	ds_read_b128 v[144:147], v156
	ds_read_b128 v[148:151], v156 offset:1024
	ds_read_b128 v[152:155], v156 offset:2048
	ds_read_b128 v[156:159], v156 offset:3072
	s_add_u32 s24, s66, 0x80000
	s_addc_u32 s25, s67, 0
	s_mov_b32 m0, s77
	v_lshl_add_u64 v[216:217], s[24:25], 0, v[166:167]
	ds_read_b128 v[178:181], v162 offset:32768
	ds_read_b128 v[182:185], v162 offset:33792
	ds_read_b128 v[186:189], v162 offset:34816
	ds_read_b128 v[190:193], v162 offset:35840
	ds_read_b128 v[194:197], v162 offset:36864
	ds_read_b128 v[198:201], v162 offset:37888
	ds_read_b128 v[202:205], v162 offset:38912
	ds_read_b128 v[206:209], v162 offset:39936
	global_load_lds_dwordx4 v[216:217], off
	v_lshl_add_u64 v[216:217], s[24:25], 0, v[170:171]
	s_mov_b32 m0, s78
	s_nop 0
	global_load_lds_dwordx4 v[216:217], off
	s_waitcnt vmcnt(8)
	s_waitcnt lgkmcnt(0)
	s_barrier
	s_setprio 1
	s_waitcnt lgkmcnt(0)
	v_mfma_f32_16x16x32_bf16 v[124:127], v[128:131], v[178:181], v[124:127]
	v_mfma_f32_16x16x32_bf16 v[120:123], v[136:139], v[178:181], v[120:123]
	v_mfma_f32_16x16x32_bf16 v[108:111], v[128:131], v[186:189], v[108:111]
	v_mfma_f32_16x16x32_bf16 v[104:107], v[136:139], v[186:189], v[104:107]
	v_mfma_f32_16x16x32_bf16 v[92:95], v[128:131], v[194:197], v[92:95]
	v_mfma_f32_16x16x32_bf16 v[88:91], v[136:139], v[194:197], v[88:91]
	v_mfma_f32_16x16x32_bf16 v[76:79], v[128:131], v[202:205], v[76:79]
	v_mfma_f32_16x16x32_bf16 v[72:75], v[136:139], v[202:205], v[72:75]
	v_mfma_f32_16x16x32_bf16 v[124:127], v[132:135], v[182:185], v[124:127]
	v_mfma_f32_16x16x32_bf16 v[120:123], v[140:143], v[182:185], v[120:123]
	v_mfma_f32_16x16x32_bf16 v[108:111], v[132:135], v[190:193], v[108:111]
	v_mfma_f32_16x16x32_bf16 v[104:107], v[140:143], v[190:193], v[104:107]
	v_mfma_f32_16x16x32_bf16 v[92:95], v[132:135], v[198:201], v[92:95]
	v_mfma_f32_16x16x32_bf16 v[88:91], v[140:143], v[198:201], v[88:91]
	v_mfma_f32_16x16x32_bf16 v[76:79], v[132:135], v[206:209], v[76:79]
	v_mfma_f32_16x16x32_bf16 v[72:75], v[140:143], v[206:209], v[72:75]
	s_setprio 0
	s_setprio 1
	v_mfma_f32_16x16x32_bf16 v[116:119], v[144:147], v[178:181], v[116:119]
	v_mfma_f32_16x16x32_bf16 v[112:115], v[152:155], v[178:181], v[112:115]
	v_mfma_f32_16x16x32_bf16 v[100:103], v[144:147], v[186:189], v[100:103]
	v_mfma_f32_16x16x32_bf16 v[96:99], v[152:155], v[186:189], v[96:99]
	v_mfma_f32_16x16x32_bf16 v[84:87], v[144:147], v[194:197], v[84:87]
	v_mfma_f32_16x16x32_bf16 v[80:83], v[152:155], v[194:197], v[80:83]
	v_mfma_f32_16x16x32_bf16 v[68:71], v[144:147], v[202:205], v[68:71]
	v_mfma_f32_16x16x32_bf16 v[64:67], v[152:155], v[202:205], v[64:67]
	v_mfma_f32_16x16x32_bf16 v[116:119], v[148:151], v[182:185], v[116:119]
	v_mfma_f32_16x16x32_bf16 v[112:115], v[156:159], v[182:185], v[112:115]
	v_mfma_f32_16x16x32_bf16 v[100:103], v[148:151], v[190:193], v[100:103]
	v_mfma_f32_16x16x32_bf16 v[96:99], v[156:159], v[190:193], v[96:99]
	v_mfma_f32_16x16x32_bf16 v[84:87], v[148:151], v[198:201], v[84:87]
	v_mfma_f32_16x16x32_bf16 v[80:83], v[156:159], v[198:201], v[80:83]
	v_mfma_f32_16x16x32_bf16 v[68:71], v[148:151], v[206:209], v[68:71]
	v_mfma_f32_16x16x32_bf16 v[64:67], v[156:159], v[206:209], v[64:67]
	s_setprio 0
	s_barrier
; #define PG8_STAGE(bufoff, gbase, voff) do { _Pragma("unroll") for (int _i = 0; _i < 2; ++_i) \
;         __builtin_amdgcn_global_load_lds((const unsigned*)((const char*)(gbase) + (voff)[_i]), (PG8_LAS unsigned*)(lds + (bufoff) + ldsw + _i * 8192), 16, 0, 0); } while (0)
; #define PG8_LDA(dst, b, h) do { _Pragma("unroll") for (int m = 0; m < 4; ++m) _Pragma("unroll") for (int k = 0; k < 2; ++k) dst[m][k] = *(const PG8_LAS bf16x8*)(lds + PG8_SA(b, h) + aoff + m * 2048 + k * 1024); } while (0)
; #define PG8_MMA(ai, bj, At, Bt) do { __builtin_amdgcn_s_setprio(1); _Pragma("unroll") for (int m = 0; m < 4; ++m) _Pragma("unroll") for (int n = 0; n < 2; ++n) _Pragma("unroll") for (int k = 0; k < 2; ++k) \
;         acc[ai][bj][m][n] = __builtin_amdgcn_mfma_f32_16x16x32_bf16(Bt[n][k], At[m][k], acc[ai][bj][m][n], 0, 0, 0); __builtin_amdgcn_s_setprio(0); } while (0)
; #define PG8_WAIT_V(n) asm volatile("s_waitcnt vmcnt(" #n ")" ::: "memory")
; #define PG8_WAIT_L(n) asm volatile("s_waitcnt lgkmcnt(" #n ")" ::: "memory")
; #define PG8_BAR __builtin_amdgcn_s_barrier()
; #define PG8_SCHED __builtin_amdgcn_sched_barrier(0)
; template <class Epi, class Sched, bool ALIGN_EPI = false, bool SP2 = false>
; __device__ __forceinline__ void gemm_phase(PG8_LAS unsigned char* lds, const Gemm g, const Sched& S, const Epi& E, const int wid_in) {
;     ...
;         for (int t = 0; t < nt; t += 2) {
;             const bool last = (t == nt - 2);
;     ...
;             PG8_WAIT_V(8); PG8_WAIT_L(0); PG8_BAR; PG8_MMA(0, 0, At, B0); PG8_MMA(0, 1, At, B1); PG8_BAR; PG8_SCHED;
;             PG8_LDA(At, 1, 1); PG8_STAGE(PG8_SB(1, 0), b3, voffB); PG8_STAGE(PG8_SB(1, 1), b3 + hstep, voffB); PG8_STAGE(PG8_SA(1, 0), a3, voffA);
;             PG8_WAIT_V(8); PG8_WAIT_L(0); PG8_BAR; PG8_MMA(1, 0, At, B0); PG8_MMA(1, 1, At, B1); PG8_BAR; PG8_SCHED;
	s_add_i32 s24, s26, s74
	v_lshl_add_u64 v[164:165], v[164:165], 0, s[8:9]
	s_mov_b32 m0, s24
	ds_read_b128 v[178:181], v162 offset:49152
	ds_read_b128 v[182:185], v162 offset:50176
	ds_read_b128 v[186:189], v162 offset:51200
	ds_read_b128 v[190:193], v162 offset:52224
	ds_read_b128 v[194:197], v162 offset:53248
	ds_read_b128 v[198:201], v162 offset:54272
	ds_read_b128 v[202:205], v162 offset:55296
	ds_read_b128 v[206:209], v162 offset:56320
	global_load_lds_dwordx4 v[164:165], off
	s_add_i32 m0, s24, 0x2000
	s_add_u32 s24, s64, 0x80080
	v_lshl_add_u64 v[164:165], v[210:211], 0, s[8:9]
	s_addc_u32 s25, s65, 0
	s_add_i32 s26, s27, s74
	global_load_lds_dwordx4 v[164:165], off
	v_lshl_add_u64 v[164:165], s[24:25], 0, v[168:169]
	s_mov_b32 m0, s26
	s_nop 0
	global_load_lds_dwordx4 v[164:165], off
	v_lshl_add_u64 v[164:165], s[24:25], 0, v[172:173]
	s_add_i32 m0, s26, 0x2000
	s_nop 0
	global_load_lds_dwordx4 v[164:165], off
	v_lshl_add_u64 v[164:165], v[212:213], 0, s[8:9]
	s_mov_b32 m0, s80
	s_nop 0
	global_load_lds_dwordx4 v[164:165], off
	v_lshl_add_u64 v[164:165], v[214:215], 0, s[8:9]
	s_mov_b32 m0, s81
	s_nop 0
	global_load_lds_dwordx4 v[164:165], off
	s_waitcnt vmcnt(8)
	s_waitcnt lgkmcnt(0)
	s_barrier
	s_setprio 1
	s_waitcnt lgkmcnt(0)
	v_mfma_f32_16x16x32_bf16 v[60:63], v[128:131], v[178:181], v[60:63]
	v_mfma_f32_16x16x32_bf16 v[56:59], v[136:139], v[178:181], v[56:59]
	v_mfma_f32_16x16x32_bf16 v[44:47], v[128:131], v[186:189], v[44:47]
	v_mfma_f32_16x16x32_bf16 v[40:43], v[136:139], v[186:189], v[40:43]
	v_mfma_f32_16x16x32_bf16 v[28:31], v[128:131], v[194:197], v[28:31]
	v_mfma_f32_16x16x32_bf16 v[24:27], v[136:139], v[194:197], v[24:27]
	v_mfma_f32_16x16x32_bf16 v[12:15], v[128:131], v[202:205], v[12:15]
	v_mfma_f32_16x16x32_bf16 v[8:11], v[136:139], v[202:205], v[8:11]
	v_mfma_f32_16x16x32_bf16 v[60:63], v[132:135], v[182:185], v[60:63]
	v_mfma_f32_16x16x32_bf16 v[56:59], v[140:143], v[182:185], v[56:59]
	v_mfma_f32_16x16x32_bf16 v[44:47], v[132:135], v[190:193], v[44:47]
	v_mfma_f32_16x16x32_bf16 v[40:43], v[140:143], v[190:193], v[40:43]
	v_mfma_f32_16x16x32_bf16 v[28:31], v[132:135], v[198:201], v[28:31]
	v_mfma_f32_16x16x32_bf16 v[24:27], v[140:143], v[198:201], v[24:27]
	v_mfma_f32_16x16x32_bf16 v[12:15], v[132:135], v[206:209], v[12:15]
	v_mfma_f32_16x16x32_bf16 v[8:11], v[140:143], v[206:209], v[8:11]
	s_setprio 0
	s_setprio 1
	v_mfma_f32_16x16x32_bf16 v[52:55], v[144:147], v[178:181], v[52:55]
	v_mfma_f32_16x16x32_bf16 v[48:51], v[152:155], v[178:181], v[48:51]
	v_mfma_f32_16x16x32_bf16 v[36:39], v[144:147], v[186:189], v[36:39]
	v_mfma_f32_16x16x32_bf16 v[32:35], v[152:155], v[186:189], v[32:35]
	v_mfma_f32_16x16x32_bf16 v[20:23], v[144:147], v[194:197], v[20:23]
	v_mfma_f32_16x16x32_bf16 v[16:19], v[152:155], v[194:197], v[16:19]
	v_mfma_f32_16x16x32_bf16 v[4:7], v[144:147], v[202:205], v[4:7]
	v_mfma_f32_16x16x32_bf16 v[0:3], v[152:155], v[202:205], v[0:3]
	v_mfma_f32_16x16x32_bf16 v[52:55], v[148:151], v[182:185], v[52:55]
	v_mfma_f32_16x16x32_bf16 v[48:51], v[156:159], v[182:185], v[48:51]
	v_mfma_f32_16x16x32_bf16 v[36:39], v[148:151], v[190:193], v[36:39]
	v_mfma_f32_16x16x32_bf16 v[32:35], v[156:159], v[190:193], v[32:35]
	v_mfma_f32_16x16x32_bf16 v[20:23], v[148:151], v[198:201], v[20:23]
	v_mfma_f32_16x16x32_bf16 v[16:19], v[156:159], v[198:201], v[16:19]
	v_mfma_f32_16x16x32_bf16 v[4:7], v[148:151], v[206:209], v[4:7]
	v_mfma_f32_16x16x32_bf16 v[0:3], v[156:159], v[206:209], v[0:3]
	s_setprio 0
	s_add_i32 s39, s39, 2
	s_add_u32 s62, s62, 0x100
	s_addc_u32 s63, s63, 0
	s_add_u32 s34, s34, 0x100
	s_addc_u32 s35, s35, 0
	s_cmp_gt_u32 s39, 29
	s_barrier
	s_cbranch_scc0 .LBB0_814
	s_and_b64 vcc, exec, s[52:53]
	s_cbranch_vccz .LBB0_817
	s_barrier

; #define PG8_STAGE(bufoff, gbase, voff) do { _Pragma("unroll") for (int _i = 0; _i < 2; ++_i) \
;         __builtin_amdgcn_global_load_lds((const unsigned*)((const char*)(gbase) + (voff)[_i]), (PG8_LAS unsigned*)(lds + (bufoff) + ldsw + _i * 8192), 16, 0, 0); } while (0)
; #define PG8_LDA(dst, b, h) do { _Pragma("unroll") for (int m = 0; m < 4; ++m) _Pragma("unroll") for (int k = 0; k < 2; ++k) dst[m][k] = *(const PG8_LAS bf16x8*)(lds + PG8_SA(b, h) + aoff + m * 2048 + k * 1024); } while (0)
; #define PG8_LDB(dst, b, h) do { _Pragma("unroll") for (int n = 0; n < 2; ++n) _Pragma("unroll") for (int k = 0; k < 2; ++k) dst[n][k] = *(const PG8_LAS bf16x8*)(lds + PG8_SB(b, h) + boff + n * 2048 + k * 1024); } while (0)
; #define PG8_MMA(ai, bj, At, Bt) do { __builtin_amdgcn_s_setprio(1); _Pragma("unroll") for (int m = 0; m < 4; ++m) _Pragma("unroll") for (int n = 0; n < 2; ++n) _Pragma("unroll") for (int k = 0; k < 2; ++k) \
;         acc[ai][bj][m][n] = __builtin_amdgcn_mfma_f32_16x16x32_bf16(Bt[n][k], At[m][k], acc[ai][bj][m][n], 0, 0, 0); __builtin_amdgcn_s_setprio(0); } while (0)
; #define PG8_WAIT_V(n) asm volatile("s_waitcnt vmcnt(" #n ")" ::: "memory")
; #define PG8_WAIT_L(n) asm volatile("s_waitcnt lgkmcnt(" #n ")" ::: "memory")
; #define PG8_BAR __builtin_amdgcn_s_barrier()
; template <class Epi, class Sched, bool ALIGN_EPI = false, bool SP2 = false>
; __device__ __forceinline__ void gemm_phase(PG8_LAS unsigned char* lds, const Gemm g, const Sched& S, const Epi& E, const int wid_in) {
;     ...
;         for (int t = 0; t < nt; t += 2) {
;             const bool last = (t == nt - 2);
;             const char* a1 = cA + (size_t)(t + 1) * kstep;
;             const char* a2 = last ? nA : cA + (size_t)(t + 2) * kstep; const char* b2 = last ? nB : cB + (size_t)(t + 2) * kstep;
;             const char* a3 = a2 + kstep; const char* b3 = b2 + kstep;
;             if (last && has_next) S.a_ready(nxt);
;             if constexpr (SP2) {
;             PG8_LDB(B0, 0, 0); PG8_LDB(B1, 0, 1); PG8_SCHED; PG8_LDA(At, 0, 0); PG8_STAGE(PG8_SA(1, 1), a1 + hstep, voffA);
;             PG8_WAIT_V(8); PG8_WAIT_L(0); PG8_BAR; PG8_MMA(0, 0, At, B0); PG8_MMA(0, 1, At, B1); PG8_BAR; PG8_SCHED;
;             PG8_LDA(At, 0, 1); PG8_STAGE(PG8_SB(0, 0), b2, voffB); PG8_STAGE(PG8_SB(0, 1), b2 + hstep, voffB); PG8_STAGE(PG8_SA(0, 0), a2, voffA);
.LBB0_1009:
	s_add_u32 s42, s54, 0x100
	s_addc_u32 s43, s55, 0
	s_add_i32 s24, 0, 0x10000
	s_cmpk_eq_i32 s18, 0x54
	s_cselect_b32 s59, s51, s43
	s_cselect_b32 s58, s50, s42
	v_add_u32_e32 v146, s24, v149
	s_cselect_b32 s57, s53, s15
	s_cselect_b32 s56, s52, s14
	s_add_i32 s26, 0, 0x14000
	ds_read_b128 v[138:141], v146
	ds_read_b128 v[142:145], v146 offset:1024
	ds_read_b128 v[152:155], v146 offset:2048
	ds_read_b128 v[156:159], v146 offset:3072
	v_add_u32_e32 v146, s26, v149
	ds_read_b128 v[162:165], v146
	ds_read_b128 v[166:169], v146 offset:1024
	ds_read_b128 v[170:173], v146 offset:2048
	ds_read_b128 v[174:177], v146 offset:3072
	v_lshl_add_u64 v[146:147], s[54:55], 0, v[134:135]
	s_add_i32 m0, s63, 0xc000
	ds_read_b128 v[178:181], v151
	ds_read_b128 v[182:185], v151 offset:1024
	ds_read_b128 v[186:189], v151 offset:2048
	ds_read_b128 v[190:193], v151 offset:3072
	ds_read_b128 v[194:197], v151 offset:4096
	ds_read_b128 v[198:201], v151 offset:5120
	ds_read_b128 v[202:205], v151 offset:6144
	ds_read_b128 v[206:209], v151 offset:7168
	global_load_lds_dwordx4 v[146:147], off
	v_lshl_add_u64 v[146:147], s[54:55], 0, v[136:137]
	s_add_i32 m0, s63, 0xe000
	s_nop 0
	global_load_lds_dwordx4 v[146:147], off
	s_waitcnt vmcnt(8)
	s_waitcnt lgkmcnt(0)
	s_barrier
	s_setprio 1
	s_waitcnt lgkmcnt(0)
	v_mfma_f32_16x16x32_bf16 v[124:127], v[138:141], v[178:181], v[124:127]
	v_mfma_f32_16x16x32_bf16 v[120:123], v[152:155], v[178:181], v[120:123]
	v_mfma_f32_16x16x32_bf16 v[108:111], v[138:141], v[186:189], v[108:111]
	v_mfma_f32_16x16x32_bf16 v[104:107], v[152:155], v[186:189], v[104:107]
	v_mfma_f32_16x16x32_bf16 v[92:95], v[138:141], v[194:197], v[92:95]
	v_mfma_f32_16x16x32_bf16 v[88:91], v[152:155], v[194:197], v[88:91]
	v_mfma_f32_16x16x32_bf16 v[76:79], v[138:141], v[202:205], v[76:79]
	v_mfma_f32_16x16x32_bf16 v[72:75], v[152:155], v[202:205], v[72:75]
	v_mfma_f32_16x16x32_bf16 v[124:127], v[142:145], v[182:185], v[124:127]
	v_mfma_f32_16x16x32_bf16 v[120:123], v[156:159], v[182:185], v[120:123]
	v_mfma_f32_16x16x32_bf16 v[108:111], v[142:145], v[190:193], v[108:111]
	v_mfma_f32_16x16x32_bf16 v[104:107], v[156:159], v[190:193], v[104:107]
	v_mfma_f32_16x16x32_bf16 v[92:95], v[142:145], v[198:201], v[92:95]
	v_mfma_f32_16x16x32_bf16 v[88:91], v[156:159], v[198:201], v[88:91]
	v_mfma_f32_16x16x32_bf16 v[76:79], v[142:145], v[206:209], v[76:79]
	v_mfma_f32_16x16x32_bf16 v[72:75], v[156:159], v[206:209], v[72:75]
	s_setprio 0
	s_setprio 1
	v_mfma_f32_16x16x32_bf16 v[116:119], v[162:165], v[178:181], v[116:119]
	v_mfma_f32_16x16x32_bf16 v[112:115], v[170:173], v[178:181], v[112:115]
	v_mfma_f32_16x16x32_bf16 v[100:103], v[162:165], v[186:189], v[100:103]
	v_mfma_f32_16x16x32_bf16 v[96:99], v[170:173], v[186:189], v[96:99]
	v_mfma_f32_16x16x32_bf16 v[84:87], v[162:165], v[194:197], v[84:87]
	v_mfma_f32_16x16x32_bf16 v[80:83], v[170:173], v[194:197], v[80:83]
	v_mfma_f32_16x16x32_bf16 v[68:71], v[162:165], v[202:205], v[68:71]
	v_mfma_f32_16x16x32_bf16 v[64:67], v[170:173], v[202:205], v[64:67]
	v_mfma_f32_16x16x32_bf16 v[116:119], v[166:169], v[182:185], v[116:119]
	v_mfma_f32_16x16x32_bf16 v[112:115], v[174:177], v[182:185], v[112:115]
	v_mfma_f32_16x16x32_bf16 v[100:103], v[166:169], v[190:193], v[100:103]
	v_mfma_f32_16x16x32_bf16 v[96:99], v[174:177], v[190:193], v[96:99]
	v_mfma_f32_16x16x32_bf16 v[84:87], v[166:169], v[198:201], v[84:87]
	v_mfma_f32_16x16x32_bf16 v[80:83], v[174:177], v[198:201], v[80:83]
	v_mfma_f32_16x16x32_bf16 v[68:71], v[166:169], v[206:209], v[68:71]
	v_mfma_f32_16x16x32_bf16 v[64:67], v[174:177], v[206:209], v[64:67]
	s_setprio 0
	s_barrier
	s_add_i32 s24, s24, s62
	v_lshl_add_u64 v[146:147], s[56:57], 0, v[160:161]
	s_mov_b32 m0, s24
	ds_read_b128 v[178:181], v151 offset:16384
	ds_read_b128 v[182:185], v151 offset:17408
	ds_read_b128 v[186:189], v151 offset:18432
	ds_read_b128 v[190:193], v151 offset:19456
	ds_read_b128 v[194:197], v151 offset:20480
	ds_read_b128 v[198:201], v151 offset:21504
	ds_read_b128 v[202:205], v151 offset:22528
	ds_read_b128 v[206:209], v151 offset:23552
	global_load_lds_dwordx4 v[146:147], off
	s_add_i32 m0, s24, 0x2000
	s_add_u32 s24, s56, 0x160000
	v_lshl_add_u64 v[210:211], s[56:57], 0, v[132:133]
	s_addc_u32 s25, s57, 0
	s_add_i32 s26, s26, s62
	global_load_lds_dwordx4 v[210:211], off
	v_lshl_add_u64 v[212:213], s[24:25], 0, v[160:161]
	s_mov_b32 m0, s26
	v_lshl_add_u64 v[214:215], s[58:59], 0, v[130:131]
	global_load_lds_dwordx4 v[212:213], off
	v_lshl_add_u64 v[212:213], s[24:25], 0, v[132:133]
	s_add_i32 m0, s26, 0x2000
	s_nop 0
	global_load_lds_dwordx4 v[212:213], off
	v_lshl_add_u64 v[212:213], s[58:59], 0, v[128:129]
	s_mov_b32 m0, s63
	s_nop 0
	global_load_lds_dwordx4 v[212:213], off
	s_mov_b32 m0, s64
	s_nop 0
	global_load_lds_dwordx4 v[214:215], off
	s_waitcnt vmcnt(8)
	s_waitcnt lgkmcnt(0)
	s_barrier
; #define PG8_STAGE(bufoff, gbase, voff) do { _Pragma("unroll") for (int _i = 0; _i < 2; ++_i) \
;         __builtin_amdgcn_global_load_lds((const unsigned*)((const char*)(gbase) + (voff)[_i]), (PG8_LAS unsigned*)(lds + (bufoff) + ldsw + _i * 8192), 16, 0, 0); } while (0)
; #define PG8_LDA(dst, b, h) do { _Pragma("unroll") for (int m = 0; m < 4; ++m) _Pragma("unroll") for (int k = 0; k < 2; ++k) dst[m][k] = *(const PG8_LAS bf16x8*)(lds + PG8_SA(b, h) + aoff + m * 2048 + k * 1024); } while (0)
; #define PG8_LDB(dst, b, h) do { _Pragma("unroll") for (int n = 0; n < 2; ++n) _Pragma("unroll") for (int k = 0; k < 2; ++k) dst[n][k] = *(const PG8_LAS bf16x8*)(lds + PG8_SB(b, h) + boff + n * 2048 + k * 1024); } while (0)
; #define PG8_MMA(ai, bj, At, Bt) do { __builtin_amdgcn_s_setprio(1); _Pragma("unroll") for (int m = 0; m < 4; ++m) _Pragma("unroll") for (int n = 0; n < 2; ++n) _Pragma("unroll") for (int k = 0; k < 2; ++k) \
;         acc[ai][bj][m][n] = __builtin_amdgcn_mfma_f32_16x16x32_bf16(Bt[n][k], At[m][k], acc[ai][bj][m][n], 0, 0, 0); __builtin_amdgcn_s_setprio(0); } while (0)
; #define PG8_WAIT_V(n) asm volatile("s_waitcnt vmcnt(" #n ")" ::: "memory")
; #define PG8_WAIT_L(n) asm volatile("s_waitcnt lgkmcnt(" #n ")" ::: "memory")
; #define PG8_BAR __builtin_amdgcn_s_barrier()
; #define PG8_SCHED __builtin_amdgcn_sched_barrier(0)
; template <class Epi, class Sched, bool ALIGN_EPI = false, bool SP2 = false>
; __device__ __forceinline__ void gemm_phase(PG8_LAS unsigned char* lds, const Gemm g, const Sched& S, const Epi& E, const int wid_in) {
;     ...
;             PG8_WAIT_V(8); PG8_WAIT_L(0); PG8_BAR; PG8_MMA(1, 0, At, B0); PG8_MMA(1, 1, At, B1); PG8_BAR; PG8_SCHED;
;             PG8_LDB(B0, 1, 0); PG8_LDB(B1, 1, 1); PG8_SCHED; PG8_LDA(At, 1, 0); PG8_STAGE(PG8_SA(0, 1), a2 + hstep, voffA);
;             PG8_WAIT_V(8); PG8_WAIT_L(0); PG8_BAR; PG8_MMA(0, 0, At, B0); PG8_MMA(0, 1, At, B1); PG8_BAR; PG8_SCHED;
	s_setprio 1
	s_waitcnt lgkmcnt(0)
	v_mfma_f32_16x16x32_bf16 v[60:63], v[138:141], v[178:181], v[60:63]
	v_mfma_f32_16x16x32_bf16 v[56:59], v[152:155], v[178:181], v[56:59]
	v_mfma_f32_16x16x32_bf16 v[44:47], v[138:141], v[186:189], v[44:47]
	v_mfma_f32_16x16x32_bf16 v[40:43], v[152:155], v[186:189], v[40:43]
	v_mfma_f32_16x16x32_bf16 v[28:31], v[138:141], v[194:197], v[28:31]
	v_mfma_f32_16x16x32_bf16 v[24:27], v[152:155], v[194:197], v[24:27]
	v_mfma_f32_16x16x32_bf16 v[12:15], v[138:141], v[202:205], v[12:15]
	v_mfma_f32_16x16x32_bf16 v[8:11], v[152:155], v[202:205], v[8:11]
	v_mfma_f32_16x16x32_bf16 v[60:63], v[142:145], v[182:185], v[60:63]
	v_mfma_f32_16x16x32_bf16 v[56:59], v[156:159], v[182:185], v[56:59]
	v_mfma_f32_16x16x32_bf16 v[44:47], v[142:145], v[190:193], v[44:47]
	v_mfma_f32_16x16x32_bf16 v[40:43], v[156:159], v[190:193], v[40:43]
	v_mfma_f32_16x16x32_bf16 v[28:31], v[142:145], v[198:201], v[28:31]
	v_mfma_f32_16x16x32_bf16 v[24:27], v[156:159], v[198:201], v[24:27]
	v_mfma_f32_16x16x32_bf16 v[12:15], v[142:145], v[206:209], v[12:15]
	v_mfma_f32_16x16x32_bf16 v[8:11], v[156:159], v[206:209], v[8:11]
	s_setprio 0
	s_setprio 1
	v_mfma_f32_16x16x32_bf16 v[52:55], v[162:165], v[178:181], v[52:55]
	v_mfma_f32_16x16x32_bf16 v[48:51], v[170:173], v[178:181], v[48:51]
	v_mfma_f32_16x16x32_bf16 v[36:39], v[162:165], v[186:189], v[36:39]
	v_mfma_f32_16x16x32_bf16 v[32:35], v[170:173], v[186:189], v[32:35]
	v_mfma_f32_16x16x32_bf16 v[20:23], v[162:165], v[194:197], v[20:23]
	v_mfma_f32_16x16x32_bf16 v[16:19], v[170:173], v[194:197], v[16:19]
	v_mfma_f32_16x16x32_bf16 v[4:7], v[162:165], v[202:205], v[4:7]
	v_mfma_f32_16x16x32_bf16 v[0:3], v[170:173], v[202:205], v[0:3]
	v_mfma_f32_16x16x32_bf16 v[52:55], v[166:169], v[182:185], v[52:55]
	v_mfma_f32_16x16x32_bf16 v[48:51], v[174:177], v[182:185], v[48:51]
	v_mfma_f32_16x16x32_bf16 v[36:39], v[166:169], v[190:193], v[36:39]
	v_mfma_f32_16x16x32_bf16 v[32:35], v[174:177], v[190:193], v[32:35]
	v_mfma_f32_16x16x32_bf16 v[20:23], v[166:169], v[198:201], v[20:23]
	v_mfma_f32_16x16x32_bf16 v[16:19], v[174:177], v[198:201], v[16:19]
	v_mfma_f32_16x16x32_bf16 v[4:7], v[166:169], v[206:209], v[4:7]
	v_mfma_f32_16x16x32_bf16 v[0:3], v[174:177], v[206:209], v[0:3]
	s_setprio 0
	s_barrier
	s_add_i32 s26, 0, 0x18000
	s_add_i32 s27, 0, 0x1c000
	v_add_u32_e32 v156, s26, v149
	v_add_u32_e32 v174, s27, v149
	ds_read_b128 v[138:141], v156
	ds_read_b128 v[142:145], v156 offset:1024
	ds_read_b128 v[152:155], v156 offset:2048
	ds_read_b128 v[156:159], v156 offset:3072
	ds_read_b128 v[162:165], v174
	ds_read_b128 v[166:169], v174 offset:1024
	ds_read_b128 v[170:173], v174 offset:2048
	ds_read_b128 v[174:177], v174 offset:3072
	s_add_u32 s24, s58, 0x160000
	s_addc_u32 s25, s59, 0
	s_mov_b32 m0, s65
	v_lshl_add_u64 v[216:217], s[24:25], 0, v[128:129]
	ds_read_b128 v[178:181], v151 offset:32768
	ds_read_b128 v[182:185], v151 offset:33792
	ds_read_b128 v[186:189], v151 offset:34816
	ds_read_b128 v[190:193], v151 offset:35840
	ds_read_b128 v[194:197], v151 offset:36864
	ds_read_b128 v[198:201], v151 offset:37888
	ds_read_b128 v[202:205], v151 offset:38912
	ds_read_b128 v[206:209], v151 offset:39936
	global_load_lds_dwordx4 v[216:217], off
	v_lshl_add_u64 v[216:217], s[24:25], 0, v[130:131]
	s_mov_b32 m0, s66
	s_nop 0
	global_load_lds_dwordx4 v[216:217], off
	s_waitcnt vmcnt(8)
	s_waitcnt lgkmcnt(0)
	s_barrier
	s_setprio 1
	s_waitcnt lgkmcnt(0)
	v_mfma_f32_16x16x32_bf16 v[124:127], v[138:141], v[178:181], v[124:127]
	v_mfma_f32_16x16x32_bf16 v[120:123], v[152:155], v[178:181], v[120:123]
	v_mfma_f32_16x16x32_bf16 v[108:111], v[138:141], v[186:189], v[108:111]
	v_mfma_f32_16x16x32_bf16 v[104:107], v[152:155], v[186:189], v[104:107]
	v_mfma_f32_16x16x32_bf16 v[92:95], v[138:141], v[194:197], v[92:95]
	v_mfma_f32_16x16x32_bf16 v[88:91], v[152:155], v[194:197], v[88:91]
	v_mfma_f32_16x16x32_bf16 v[76:79], v[138:141], v[202:205], v[76:79]
	v_mfma_f32_16x16x32_bf16 v[72:75], v[152:155], v[202:205], v[72:75]
	v_mfma_f32_16x16x32_bf16 v[124:127], v[142:145], v[182:185], v[124:127]
	v_mfma_f32_16x16x32_bf16 v[120:123], v[156:159], v[182:185], v[120:123]
	v_mfma_f32_16x16x32_bf16 v[108:111], v[142:145], v[190:193], v[108:111]
	v_mfma_f32_16x16x32_bf16 v[104:107], v[156:159], v[190:193], v[104:107]
	v_mfma_f32_16x16x32_bf16 v[92:95], v[142:145], v[198:201], v[92:95]
	v_mfma_f32_16x16x32_bf16 v[88:91], v[156:159], v[198:201], v[88:91]
	v_mfma_f32_16x16x32_bf16 v[76:79], v[142:145], v[206:209], v[76:79]
	v_mfma_f32_16x16x32_bf16 v[72:75], v[156:159], v[206:209], v[72:75]
	s_setprio 0
	s_setprio 1
	v_mfma_f32_16x16x32_bf16 v[116:119], v[162:165], v[178:181], v[116:119]
	v_mfma_f32_16x16x32_bf16 v[112:115], v[170:173], v[178:181], v[112:115]
	v_mfma_f32_16x16x32_bf16 v[100:103], v[162:165], v[186:189], v[100:103]
	v_mfma_f32_16x16x32_bf16 v[96:99], v[170:173], v[186:189], v[96:99]
	v_mfma_f32_16x16x32_bf16 v[84:87], v[162:165], v[194:197], v[84:87]
	v_mfma_f32_16x16x32_bf16 v[80:83], v[170:173], v[194:197], v[80:83]
	v_mfma_f32_16x16x32_bf16 v[68:71], v[162:165], v[202:205], v[68:71]
	v_mfma_f32_16x16x32_bf16 v[64:67], v[170:173], v[202:205], v[64:67]
	v_mfma_f32_16x16x32_bf16 v[116:119], v[166:169], v[182:185], v[116:119]
	v_mfma_f32_16x16x32_bf16 v[112:115], v[174:177], v[182:185], v[112:115]
	v_mfma_f32_16x16x32_bf16 v[100:103], v[166:169], v[190:193], v[100:103]
	v_mfma_f32_16x16x32_bf16 v[96:99], v[174:177], v[190:193], v[96:99]
	v_mfma_f32_16x16x32_bf16 v[84:87], v[166:169], v[198:201], v[84:87]
	v_mfma_f32_16x16x32_bf16 v[80:83], v[174:177], v[198:201], v[80:83]
	v_mfma_f32_16x16x32_bf16 v[68:71], v[166:169], v[206:209], v[68:71]
	v_mfma_f32_16x16x32_bf16 v[64:67], v[174:177], v[206:209], v[64:67]
	s_setprio 0
	s_barrier
; #define PG8_STAGE(bufoff, gbase, voff) do { _Pragma("unroll") for (int _i = 0; _i < 2; ++_i) \
;         __builtin_amdgcn_global_load_lds((const unsigned*)((const char*)(gbase) + (voff)[_i]), (PG8_LAS unsigned*)(lds + (bufoff) + ldsw + _i * 8192), 16, 0, 0); } while (0)
; #define PG8_LDA(dst, b, h) do { _Pragma("unroll") for (int m = 0; m < 4; ++m) _Pragma("unroll") for (int k = 0; k < 2; ++k) dst[m][k] = *(const PG8_LAS bf16x8*)(lds + PG8_SA(b, h) + aoff + m * 2048 + k * 1024); } while (0)
; #define PG8_MMA(ai, bj, At, Bt) do { __builtin_amdgcn_s_setprio(1); _Pragma("unroll") for (int m = 0; m < 4; ++m) _Pragma("unroll") for (int n = 0; n < 2; ++n) _Pragma("unroll") for (int k = 0; k < 2; ++k) \
;         acc[ai][bj][m][n] = __builtin_amdgcn_mfma_f32_16x16x32_bf16(Bt[n][k], At[m][k], acc[ai][bj][m][n], 0, 0, 0); __builtin_amdgcn_s_setprio(0); } while (0)
; #define PG8_WAIT_V(n) asm volatile("s_waitcnt vmcnt(" #n ")" ::: "memory")
; #define PG8_WAIT_L(n) asm volatile("s_waitcnt lgkmcnt(" #n ")" ::: "memory")
; #define PG8_BAR __builtin_amdgcn_s_barrier()
; #define PG8_SCHED __builtin_amdgcn_sched_barrier(0)
; template <class Epi, class Sched, bool ALIGN_EPI = false, bool SP2 = false>
; __device__ __forceinline__ void gemm_phase(PG8_LAS unsigned char* lds, const Gemm g, const Sched& S, const Epi& E, const int wid_in) {
;     ...
;         for (int t = 0; t < nt; t += 2) {
;             const bool last = (t == nt - 2);
;     ...
;             PG8_WAIT_V(8); PG8_WAIT_L(0); PG8_BAR; PG8_MMA(0, 0, At, B0); PG8_MMA(0, 1, At, B1); PG8_BAR; PG8_SCHED;
;             PG8_LDA(At, 1, 1); PG8_STAGE(PG8_SB(1, 0), b3, voffB); PG8_STAGE(PG8_SB(1, 1), b3 + hstep, voffB); PG8_STAGE(PG8_SA(1, 0), a3, voffA);
;             PG8_WAIT_V(8); PG8_WAIT_L(0); PG8_BAR; PG8_MMA(1, 0, At, B0); PG8_MMA(1, 1, At, B1); PG8_BAR; PG8_SCHED;
	s_add_i32 s24, s26, s62
	v_lshl_add_u64 v[146:147], v[146:147], 0, s[8:9]
	s_mov_b32 m0, s24
	ds_read_b128 v[178:181], v151 offset:49152
	ds_read_b128 v[182:185], v151 offset:50176
	ds_read_b128 v[186:189], v151 offset:51200
	ds_read_b128 v[190:193], v151 offset:52224
	ds_read_b128 v[194:197], v151 offset:53248
	ds_read_b128 v[198:201], v151 offset:54272
	ds_read_b128 v[202:205], v151 offset:55296
	ds_read_b128 v[206:209], v151 offset:56320
	global_load_lds_dwordx4 v[146:147], off
	s_add_i32 m0, s24, 0x2000
	s_add_u32 s24, s56, 0x160080
	v_lshl_add_u64 v[146:147], v[210:211], 0, s[8:9]
	s_addc_u32 s25, s57, 0
	s_add_i32 s26, s27, s62
	global_load_lds_dwordx4 v[146:147], off
	v_lshl_add_u64 v[146:147], s[24:25], 0, v[160:161]
	s_mov_b32 m0, s26
	s_nop 0
	global_load_lds_dwordx4 v[146:147], off
	v_lshl_add_u64 v[146:147], s[24:25], 0, v[132:133]
	s_add_i32 m0, s26, 0x2000
	s_nop 0
	global_load_lds_dwordx4 v[146:147], off
	v_lshl_add_u64 v[146:147], v[212:213], 0, s[8:9]
	s_mov_b32 m0, s68
	s_nop 0
	global_load_lds_dwordx4 v[146:147], off
	v_lshl_add_u64 v[146:147], v[214:215], 0, s[8:9]
	s_mov_b32 m0, s69
	s_nop 0
	global_load_lds_dwordx4 v[146:147], off
	s_waitcnt vmcnt(8)
	s_waitcnt lgkmcnt(0)
	s_barrier
	s_setprio 1
	s_waitcnt lgkmcnt(0)
	v_mfma_f32_16x16x32_bf16 v[60:63], v[138:141], v[178:181], v[60:63]
	v_mfma_f32_16x16x32_bf16 v[56:59], v[152:155], v[178:181], v[56:59]
	v_mfma_f32_16x16x32_bf16 v[44:47], v[138:141], v[186:189], v[44:47]
	v_mfma_f32_16x16x32_bf16 v[40:43], v[152:155], v[186:189], v[40:43]
	v_mfma_f32_16x16x32_bf16 v[28:31], v[138:141], v[194:197], v[28:31]
	v_mfma_f32_16x16x32_bf16 v[24:27], v[152:155], v[194:197], v[24:27]
	v_mfma_f32_16x16x32_bf16 v[12:15], v[138:141], v[202:205], v[12:15]
	v_mfma_f32_16x16x32_bf16 v[8:11], v[152:155], v[202:205], v[8:11]
	v_mfma_f32_16x16x32_bf16 v[60:63], v[142:145], v[182:185], v[60:63]
	v_mfma_f32_16x16x32_bf16 v[56:59], v[156:159], v[182:185], v[56:59]
	v_mfma_f32_16x16x32_bf16 v[44:47], v[142:145], v[190:193], v[44:47]
	v_mfma_f32_16x16x32_bf16 v[40:43], v[156:159], v[190:193], v[40:43]
	v_mfma_f32_16x16x32_bf16 v[28:31], v[142:145], v[198:201], v[28:31]
	v_mfma_f32_16x16x32_bf16 v[24:27], v[156:159], v[198:201], v[24:27]
	v_mfma_f32_16x16x32_bf16 v[12:15], v[142:145], v[206:209], v[12:15]
	v_mfma_f32_16x16x32_bf16 v[8:11], v[156:159], v[206:209], v[8:11]
	s_setprio 0
	s_setprio 1
	v_mfma_f32_16x16x32_bf16 v[52:55], v[162:165], v[178:181], v[52:55]
	v_mfma_f32_16x16x32_bf16 v[48:51], v[170:173], v[178:181], v[48:51]
	v_mfma_f32_16x16x32_bf16 v[36:39], v[162:165], v[186:189], v[36:39]
	v_mfma_f32_16x16x32_bf16 v[32:35], v[170:173], v[186:189], v[32:35]
	v_mfma_f32_16x16x32_bf16 v[20:23], v[162:165], v[194:197], v[20:23]
	v_mfma_f32_16x16x32_bf16 v[16:19], v[170:173], v[194:197], v[16:19]
	v_mfma_f32_16x16x32_bf16 v[4:7], v[162:165], v[202:205], v[4:7]
	v_mfma_f32_16x16x32_bf16 v[0:3], v[170:173], v[202:205], v[0:3]
	v_mfma_f32_16x16x32_bf16 v[52:55], v[166:169], v[182:185], v[52:55]
	v_mfma_f32_16x16x32_bf16 v[48:51], v[174:177], v[182:185], v[48:51]
	v_mfma_f32_16x16x32_bf16 v[36:39], v[166:169], v[190:193], v[36:39]
	v_mfma_f32_16x16x32_bf16 v[32:35], v[174:177], v[190:193], v[32:35]
	v_mfma_f32_16x16x32_bf16 v[20:23], v[166:169], v[198:201], v[20:23]
	v_mfma_f32_16x16x32_bf16 v[16:19], v[174:177], v[198:201], v[16:19]
	v_mfma_f32_16x16x32_bf16 v[4:7], v[166:169], v[206:209], v[4:7]
	v_mfma_f32_16x16x32_bf16 v[0:3], v[174:177], v[206:209], v[0:3]
	s_setprio 0
	s_add_i32 s18, s18, 2
	s_add_u32 s14, s14, 0x100
	s_addc_u32 s15, s15, 0
	s_cmpk_gt_u32 s18, 0x55
	s_mov_b64 s[54:55], s[42:43]
	s_barrier
	s_cbranch_scc0 .LBB0_1009
	s_and_b64 vcc, exec, s[48:49]
	s_cbranch_vccz .LBB0_1012
	s_barrier
